# combined: P0/P8 rmsnorm loops de-serialized, P0 cache_k convert loop unrolled x8, P3 subln gains via LDS, P3 QK fragment prefetch, P4 LDS-staged epilogues
# speedup vs baseline: 1.1135x; 1.0193x over previous
; __device__ __forceinline__ unsigned pk2(float lo, float hi) { f32v2_t v = {lo, hi}; bf16v2_t r = __builtin_convertvector(v, bf16v2_t); return __builtin_bit_cast(unsigned, r); }
; __device__ void phase_prep(const Params& p) {
;     ...
;   {
;     bf16_t* hb = (bf16_t*)(ws + W_B); const float* g = p.in[7];
;     for (int t = gw; t < T; t += nw) {
;       const float* x = (t < TP) ? p.in[0] + (size_t)t * DM : p.in[1] + (size_t)(t - TP) * DM;
;       f32x4 v[4]; float ss = 0.f;
; #pragma unroll
;       for (int i = 0; i < 4; ++i) { v[i] = *(const f32x4*)(x + i * 256 + lane * 4); ss += v[i][0] * v[i][0] + v[i][1] * v[i][1] + v[i][2] * v[i][2] + v[i][3] * v[i][3]; }
;       ss = wave_sum(ss);
;       const float rs = rsqrtf(ss * (1.f / DM) + EPS);
; #pragma unroll
;       for (int i = 0; i < 4; ++i) {
;         f32x4 gg = *(const f32x4*)(g + i * 256 + lane * 4);
;         u32x2 w; w.x = pk2(v[i][0] * rs * gg[0], v[i][1] * rs * gg[1]); w.y = pk2(v[i][2] * rs * gg[2], v[i][3] * rs * gg[3]);
;         *(u32x2*)(hb + (size_t)t * LDH + i * 256 + lane * 4) = w;
;       }
;     }
.LBB0_67:
	s_or_b64 exec, exec, s[0:1]
	s_mov_b64 s[62:63], exec
	v_readlane_b32 s0, v246, 4
	v_readlane_b32 s1, v246, 5
	s_and_b64 s[0:1], s[62:63], s[0:1]
	s_mov_b64 exec, s[0:1]
	s_cbranch_execz .LBB0_72
	v_and_b32_e32 v0, 64, v62
	v_add_u32_e32 v0, 64, v0
	s_waitcnt lgkmcnt(1)
	v_xor_b32_e32 v1, 32, v62
	v_cmp_lt_i32_e32 vcc, v1, v0
	s_mov_b64 s[0:1], 0
	v_mov_b64_e32 v[40:41], v[32:33]
	v_cndmask_b32_e32 v1, v62, v1, vcc
	v_lshlrev_b32_e32 v37, 2, v1
	v_xor_b32_e32 v1, 16, v62
	v_cmp_lt_i32_e32 vcc, v1, v0
	v_mov_b64_e32 v[42:43], v[24:25]
	s_nop 0
	v_cndmask_b32_e32 v1, v62, v1, vcc
	v_lshlrev_b32_e32 v39, 2, v1
	v_xor_b32_e32 v1, 8, v62
	v_cmp_lt_i32_e32 vcc, v1, v0
	s_nop 1
	v_cndmask_b32_e32 v1, v62, v1, vcc
	v_lshlrev_b32_e32 v66, 2, v1
	v_xor_b32_e32 v1, 4, v62
	v_cmp_lt_i32_e32 vcc, v1, v0
	s_nop 1
	v_cndmask_b32_e32 v1, v62, v1, vcc
	v_lshlrev_b32_e32 v67, 2, v1
	v_xor_b32_e32 v1, 2, v62
	v_cmp_lt_i32_e32 vcc, v1, v0
	s_nop 1
	v_cndmask_b32_e32 v1, v62, v1, vcc
	v_lshlrev_b32_e32 v68, 2, v1
	v_xor_b32_e32 v1, 1, v62
	v_cmp_lt_i32_e32 vcc, v1, v0
	s_nop 1
	v_cndmask_b32_e32 v0, v62, v1, vcc
	v_lshlrev_b32_e32 v69, 2, v0
	global_load_dwordx4 v[100:103], v[26:27], off
	global_load_dwordx4 v[104:107], v[26:27], off offset:1024
	global_load_dwordx4 v[108:111], v[26:27], off offset:2048
	global_load_dwordx4 v[112:115], v[26:27], off offset:3072
	s_branch .LBB0_70
.LBB0_69:
	s_or_b64 exec, exec, s[2:3]
	v_mov_b32_e32 v35, v17
	v_lshl_add_u64 v[4:5], v[0:1], 0, v[34:35]
	global_load_dwordx4 v[8:11], v[4:5], off
	s_waitcnt lgkmcnt(0)
	global_load_dwordx4 v[0:3], v[4:5], off offset:1024
	global_load_dwordx4 v[12:15], v[4:5], off offset:2048
	global_load_dwordx4 v[4:7], v[4:5], off offset:3072
	s_mov_b32 s2, 0x800000
	v_lshl_add_u64 v[42:43], v[42:43], 0, s[56:57]
	v_lshl_add_u64 v[40:41], v[40:41], 0, s[42:43]
	s_waitcnt vmcnt(3)
	v_mov_b32_e32 v74, v9
	s_waitcnt vmcnt(2)
	v_mov_b32_e32 v75, v1
	v_mov_b32_e32 v76, v8
	v_mov_b32_e32 v77, v0
	v_pk_mul_f32 v[74:75], v[74:75], v[74:75]
	s_nop 0
	v_pk_fma_f32 v[76:77], v[76:77], v[76:77], v[74:75]
	v_mov_b32_e32 v74, v10
	v_mov_b32_e32 v75, v2
	v_pk_fma_f32 v[76:77], v[74:75], v[74:75], v[76:77]
	v_mov_b32_e32 v74, v11
	v_mov_b32_e32 v75, v3
	v_pk_fma_f32 v[44:45], v[74:75], v[74:75], v[76:77]
	s_nop 0
	v_add_f32_e32 v16, v44, v45
	s_waitcnt vmcnt(1)
	v_mov_b32_e32 v72, v13
	s_waitcnt vmcnt(0)
	v_mov_b32_e32 v73, v5
	v_mov_b32_e32 v70, v12
	v_mov_b32_e32 v71, v4
	v_pk_mul_f32 v[72:73], v[72:73], v[72:73]
	s_nop 0
	v_pk_fma_f32 v[70:71], v[70:71], v[70:71], v[72:73]
	v_mov_b32_e32 v72, v14
	v_mov_b32_e32 v73, v6
	v_pk_fma_f32 v[70:71], v[72:73], v[72:73], v[70:71]
	v_mov_b32_e32 v72, v15
	v_mov_b32_e32 v73, v7
	v_pk_fma_f32 v[70:71], v[72:73], v[72:73], v[70:71]
	s_nop 0
	v_add_f32_e32 v16, v16, v70
	v_add_f32_e32 v16, v16, v71
	ds_bpermute_b32 v35, v37, v16
	s_waitcnt lgkmcnt(0)
	v_add_f32_e32 v16, v16, v35
	ds_bpermute_b32 v35, v39, v16
	s_waitcnt lgkmcnt(0)
	v_add_f32_e32 v16, v16, v35
	ds_bpermute_b32 v35, v66, v16
	s_waitcnt lgkmcnt(0)
	v_add_f32_e32 v16, v16, v35
	ds_bpermute_b32 v35, v67, v16
	s_waitcnt lgkmcnt(0)
	v_add_f32_e32 v16, v16, v35
	ds_bpermute_b32 v35, v68, v16
	s_waitcnt lgkmcnt(0)
	v_add_f32_e32 v16, v16, v35
	ds_bpermute_b32 v35, v69, v16
	s_waitcnt lgkmcnt(0)
	v_add_f32_e32 v16, v16, v35
	v_fmamk_f32 v16, v16, 0x3a800000, v55
	v_cmp_gt_f32_e32 vcc, s2, v16
	v_mul_f32_e32 v35, 0x4b800000, v16
	v_mad_u64_u32 v[44:45], s[2:3], v46, s34, v[18:19]
	v_cndmask_b32_e32 v16, v16, v35, vcc
	v_rsq_f32_e32 v16, v16
	v_mov_b32_e32 v46, v45
	v_mad_u64_u32 v[46:47], s[2:3], v47, s34, v[46:47]
	v_mul_f32_e32 v35, 0x45800000, v16
	v_cndmask_b32_e32 v16, v16, v35, vcc
	v_pk_mul_f32 v[8:9], v[8:9], v[16:17] op_sel_hi:[1,0]
	v_pk_mul_f32 v[10:11], v[10:11], v[16:17] op_sel_hi:[1,0]
	v_mov_b32_e32 v45, v46
	v_pk_mul_f32 v[0:1], v[0:1], v[16:17] op_sel_hi:[1,0]
	v_pk_mul_f32 v[2:3], v[2:3], v[16:17] op_sel_hi:[1,0]
	v_pk_mul_f32 v[4:5], v[4:5], v[16:17] op_sel_hi:[1,0]
	s_mov_b32 s2, 0x81ff
	v_cmp_lt_i32_e32 vcc, s2, v42
	s_or_b64 s[0:1], vcc, s[0:1]
	v_pk_mul_f32 v[12:13], v[12:13], v[16:17] op_sel_hi:[1,0]
	v_pk_mul_f32 v[14:15], v[14:15], v[16:17] op_sel_hi:[1,0]
	v_pk_mul_f32 v[6:7], v[6:7], v[16:17] op_sel_hi:[1,0]
	v_pk_mul_f32 v[8:9], v[100:101], v[8:9]
	v_pk_mul_f32 v[10:11], v[102:103], v[10:11]
	v_pk_mul_f32 v[0:1], v[104:105], v[0:1]
	v_pk_mul_f32 v[2:3], v[106:107], v[2:3]
	v_cvt_pk_bf16_f32 v8, v8, v9
	v_cvt_pk_bf16_f32 v9, v10, v11
	global_store_dwordx2 v[44:45], v[8:9], off
	v_pk_mul_f32 v[12:13], v[108:109], v[12:13]
	v_pk_mul_f32 v[14:15], v[110:111], v[14:15]
	v_cvt_pk_bf16_f32 v0, v0, v1
	v_cvt_pk_bf16_f32 v1, v2, v3
	global_store_dwordx2 v[44:45], v[0:1], off offset:512
	v_pk_mul_f32 v[4:5], v[112:113], v[4:5]
	v_pk_mul_f32 v[6:7], v[114:115], v[6:7]
	v_cvt_pk_bf16_f32 v12, v12, v13
	v_cvt_pk_bf16_f32 v13, v14, v15
	global_store_dwordx2 v[44:45], v[12:13], off offset:1024
	v_cvt_pk_bf16_f32 v4, v4, v5
	v_cvt_pk_bf16_f32 v5, v6, v7
	global_store_dwordx2 v[44:45], v[4:5], off offset:1536
	s_andn2_b64 exec, exec, s[0:1]
	s_cbranch_execz .LBB0_72

; __device__ __forceinline__ unsigned pk2(float lo, float hi) { f32v2_t v = {lo, hi}; bf16v2_t r = __builtin_convertvector(v, bf16v2_t); return __builtin_bit_cast(unsigned, r); }
; __device__ void phase_prep(const Params& p) {
;     ...
;   {
;     bf16_t* dk = (bf16_t*)(ws + W_D); const float* src = p.in[2];
;     for (int u = gtid; u < 8 * PAST * 256; u += gthreads) {
;       const int e = u * 4; const int row = e >> 10, c = e & 1023; const int b = row >> 11, j = row & 2047;
;       f32x4 v = *(const f32x4*)(src + (size_t)e);
;       u32x2 w; w.x = pk2(v[0], v[1]); w.y = pk2(v[2], v[3]);
;       *(u32x2*)(dk + (size_t)(TP + b * LKS + j) * LDH + c) = w;
;     }
.LBB0_74:
	s_waitcnt lgkmcnt(0)
	s_mov_b32 s54, 0x3fffff
	s_mov_b64 s[74:75], exec
	v_mov_b32_e32 v112, v2
	v_lshlrev_b32_e32 v120, 2, v0
	global_load_dwordx4 v[80:83], v120, s[68:69]
	v_add_u32_e32 v113, s60, v112
	v_lshl_add_u32 v121, s24, 2, v120
	v_cmp_ge_i32_e32 vcc, s54, v113
	s_and_b64 exec, exec, vcc
	global_load_dwordx4 v[84:87], v121, s[68:69]
	v_add_u32_e32 v114, s60, v113
	v_lshl_add_u32 v122, s24, 2, v121
	v_cmp_ge_i32_e32 vcc, s54, v114
	s_and_b64 exec, exec, vcc
	global_load_dwordx4 v[88:91], v122, s[68:69]
	v_add_u32_e32 v115, s60, v114
	v_lshl_add_u32 v123, s24, 2, v122
	v_cmp_ge_i32_e32 vcc, s54, v115
	s_and_b64 exec, exec, vcc
	global_load_dwordx4 v[92:95], v123, s[68:69]
	v_add_u32_e32 v116, s60, v115
	v_lshl_add_u32 v124, s24, 2, v123
	v_cmp_ge_i32_e32 vcc, s54, v116
	s_and_b64 exec, exec, vcc
	global_load_dwordx4 v[96:99], v124, s[68:69]
	v_add_u32_e32 v117, s60, v116
	v_lshl_add_u32 v125, s24, 2, v124
	v_cmp_ge_i32_e32 vcc, s54, v117
	s_and_b64 exec, exec, vcc
	global_load_dwordx4 v[100:103], v125, s[68:69]
	v_add_u32_e32 v118, s60, v117
	v_lshl_add_u32 v126, s24, 2, v125
	v_cmp_ge_i32_e32 vcc, s54, v118
	s_and_b64 exec, exec, vcc
	global_load_dwordx4 v[104:107], v126, s[68:69]
	v_add_u32_e32 v119, s60, v118
	v_lshl_add_u32 v127, s24, 2, v126
	v_cmp_ge_i32_e32 vcc, s54, v119
	s_and_b64 exec, exec, vcc
	global_load_dwordx4 v[108:111], v127, s[68:69]
	s_mov_b64 exec, s[74:75]
	v_ashrrev_i32_e32 v74, 19, v112
	v_bfe_u32 v75, v112, 8, 11
	v_mul_i32_i24_e32 v74, 0x840, v74
	v_add3_u32 v74, v74, v75, s6
	v_mul_lo_u32 v74, v74, s34
	v_and_b32_e32 v75, 0xff0, v120
	v_lshrrev_b32_e32 v75, 1, v75
	v_add_u32_e32 v74, v74, v75
	s_waitcnt vmcnt(7)
	v_cvt_pk_bf16_f32 v80, v80, v81
	v_cvt_pk_bf16_f32 v81, v82, v83
	global_store_dwordx2 v74, v[80:81], s[44:45]
	s_mov_b64 exec, s[74:75]
	v_cmp_ge_i32_e32 vcc, s54, v113
	s_and_b64 exec, exec, vcc
	v_ashrrev_i32_e32 v74, 19, v113
	v_bfe_u32 v75, v113, 8, 11
	v_mul_i32_i24_e32 v74, 0x840, v74
	v_add3_u32 v74, v74, v75, s6
	v_mul_lo_u32 v74, v74, s34
	v_and_b32_e32 v75, 0xff0, v121
	v_lshrrev_b32_e32 v75, 1, v75
	v_add_u32_e32 v74, v74, v75
	s_waitcnt vmcnt(7)
	v_cvt_pk_bf16_f32 v84, v84, v85
	v_cvt_pk_bf16_f32 v85, v86, v87
	global_store_dwordx2 v74, v[84:85], s[44:45]
	s_mov_b64 exec, s[74:75]
	v_cmp_ge_i32_e32 vcc, s54, v114
	s_and_b64 exec, exec, vcc
	v_ashrrev_i32_e32 v74, 19, v114
	v_bfe_u32 v75, v114, 8, 11
	v_mul_i32_i24_e32 v74, 0x840, v74
	v_add3_u32 v74, v74, v75, s6
	v_mul_lo_u32 v74, v74, s34
	v_and_b32_e32 v75, 0xff0, v122
	v_lshrrev_b32_e32 v75, 1, v75
	v_add_u32_e32 v74, v74, v75
	s_waitcnt vmcnt(7)
	v_cvt_pk_bf16_f32 v88, v88, v89
	v_cvt_pk_bf16_f32 v89, v90, v91
	global_store_dwordx2 v74, v[88:89], s[44:45]
	s_mov_b64 exec, s[74:75]
	v_cmp_ge_i32_e32 vcc, s54, v115
	s_and_b64 exec, exec, vcc
	v_ashrrev_i32_e32 v74, 19, v115
	v_bfe_u32 v75, v115, 8, 11
	v_mul_i32_i24_e32 v74, 0x840, v74
	v_add3_u32 v74, v74, v75, s6
	v_mul_lo_u32 v74, v74, s34
	v_and_b32_e32 v75, 0xff0, v123
	v_lshrrev_b32_e32 v75, 1, v75
	v_add_u32_e32 v74, v74, v75
	s_waitcnt vmcnt(7)
	v_cvt_pk_bf16_f32 v92, v92, v93
	v_cvt_pk_bf16_f32 v93, v94, v95
	global_store_dwordx2 v74, v[92:93], s[44:45]
	s_mov_b64 exec, s[74:75]
	v_cmp_ge_i32_e32 vcc, s54, v116
	s_and_b64 exec, exec, vcc
	v_ashrrev_i32_e32 v74, 19, v116
	v_bfe_u32 v75, v116, 8, 11
	v_mul_i32_i24_e32 v74, 0x840, v74
	v_add3_u32 v74, v74, v75, s6
	v_mul_lo_u32 v74, v74, s34
	v_and_b32_e32 v75, 0xff0, v124
	v_lshrrev_b32_e32 v75, 1, v75
	v_add_u32_e32 v74, v74, v75
	s_waitcnt vmcnt(7)
	v_cvt_pk_bf16_f32 v96, v96, v97
	v_cvt_pk_bf16_f32 v97, v98, v99
	global_store_dwordx2 v74, v[96:97], s[44:45]
	s_mov_b64 exec, s[74:75]
	v_cmp_ge_i32_e32 vcc, s54, v117
	s_and_b64 exec, exec, vcc
	v_ashrrev_i32_e32 v74, 19, v117
	v_bfe_u32 v75, v117, 8, 11
	v_mul_i32_i24_e32 v74, 0x840, v74
	v_add3_u32 v74, v74, v75, s6
	v_mul_lo_u32 v74, v74, s34
	v_and_b32_e32 v75, 0xff0, v125
	v_lshrrev_b32_e32 v75, 1, v75
	v_add_u32_e32 v74, v74, v75
	s_waitcnt vmcnt(7)
	v_cvt_pk_bf16_f32 v100, v100, v101
	v_cvt_pk_bf16_f32 v101, v102, v103
	global_store_dwordx2 v74, v[100:101], s[44:45]
	s_mov_b64 exec, s[74:75]
	v_cmp_ge_i32_e32 vcc, s54, v118
	s_and_b64 exec, exec, vcc
	v_ashrrev_i32_e32 v74, 19, v118
	v_bfe_u32 v75, v118, 8, 11
	v_mul_i32_i24_e32 v74, 0x840, v74
	v_add3_u32 v74, v74, v75, s6
	v_mul_lo_u32 v74, v74, s34
	v_and_b32_e32 v75, 0xff0, v126
	v_lshrrev_b32_e32 v75, 1, v75
	v_add_u32_e32 v74, v74, v75
	s_waitcnt vmcnt(7)
	v_cvt_pk_bf16_f32 v104, v104, v105
	v_cvt_pk_bf16_f32 v105, v106, v107
	global_store_dwordx2 v74, v[104:105], s[44:45]
	s_mov_b64 exec, s[74:75]
	v_cmp_ge_i32_e32 vcc, s54, v119
	s_and_b64 exec, exec, vcc
	v_ashrrev_i32_e32 v74, 19, v119
	v_bfe_u32 v75, v119, 8, 11
	v_mul_i32_i24_e32 v74, 0x840, v74
	v_add3_u32 v74, v74, v75, s6
	v_mul_lo_u32 v74, v74, s34
	v_and_b32_e32 v75, 0xff0, v127
	v_lshrrev_b32_e32 v75, 1, v75
	v_add_u32_e32 v74, v74, v75
	s_waitcnt vmcnt(7)
	v_cvt_pk_bf16_f32 v108, v108, v109
	v_cvt_pk_bf16_f32 v109, v110, v111
	global_store_dwordx2 v74, v[108:109], s[44:45]
	s_mov_b64 exec, s[74:75]
	v_add_u32_e32 v2, s60, v119
	v_lshl_add_u32 v0, s24, 2, v127
	v_lshrrev_b32_e32 v0, 2, v0
	v_cmp_ge_i32_e32 vcc, s54, v2
	s_and_b64 exec, exec, vcc
	s_cbranch_execnz .LBB0_74

; template <int MODE>
; __device__ void attn_item(const Params& p, char* lds, int grp  , int b, int h, int qblk, int dry) {
;     ...
;   const int tid = threadIdx.x, lane = tid & 63, wid = tid >> 6, hh = lane >> 5, l31 = lane & 31;
;   const int qsub = MODE == 0 ? (wid >> 1) : wid;
;   const int comp = MODE == 0 ? (wid & 1) : 0;
;   const int QB = MODE == 0 ? 64 : 128;
;   const int Lk = grp == 0 ? SEQP : LKS;
;   const int tok0 = grp == 0 ? (b * SEQ + qblk * QB) : (TP + b * 64);
;   const int qpos0 = grp == 0 ? qblk * QB : PAST;
;   const int krow0 = grp == 0 ? b * SEQ : TP + b * LKS;
;   int nkt;
;   if (grp == 0) nkt = MODE == 0 ? (qblk + 1) : (2 * qblk + 2); else nkt = 33;
;   int my_last = nkt - 1; bool active = true;
;   if (MODE == 1) { if (grp == 0) my_last = 2 * qblk + (wid >> 1); else active = (wid < 2); }
;   const int qtok = tok0 + qsub * 32 + l31;
;   const int qpos = qpos0 + qsub * 32 + l31;
;   bf16x8 qf[DQ / 16];
;   if (MODE == 0) {
;     const bf16_t* q = (const bf16_t*)(ws + W_C) + (size_t)qtok * LDH + h * 128 + comp * 64 + hh * 8;
; #pragma unroll
;     for (int ks = 0; ks < 4; ++ks) qf[ks] = *(const bf16x8*)(q + ks * 16);
;   } else {
;     const int qt = active ? qtok : tok0;
;     const bf16_t* q = (const bf16_t*)(ws + W_B) + (size_t)qt * LDH + h * 64 + hh * 8;
; #pragma unroll
;     for (int ks = 0; ks < 4; ++ks) qf[ks] = *(const bf16x8*)(q + ks * 16);
;     const bf16_t* qp = (const bf16_t*)(ws + F_ZCQ) + (size_t)qt * 512 + h * 32 + hh * 8;
;     bf16x8 a = *(const bf16x8*)(qp), c = *(const bf16x8*)(qp + 16);
; __device__ void phase_attn_diff(const Params& p, char* lds, int* s_item, int dry) {
;   const int x = blockIdx.x & 7;
;   const int total = 512 + 8;
;   unsigned* q = (unsigned*)(p.ws + W_BAR) + QW + dry * 8 + x;
;   for (;;) {
;     if (threadIdx.x == 0) *s_item = (int)__hip_atomic_fetch_add(q, 1u, __ATOMIC_RELAXED, __HIP_MEMORY_SCOPE_AGENT);
;     __syncthreads();
;     const int u = *s_item;
;     __syncthreads();
;     if (u >= total) break;
;     int grp = 0, bh, qblk = 0;
;     if (u < 256) { qblk = 63 - (u >> 3); bh = (u & 7) * 8 + x; }
;     else if (u < 264) { grp = 1; bh = (u - 256) * 8 + x; }
;     else { const int v = u - 8; qblk = 63 - (v >> 3); bh = (v & 7) * 8 + x; }
;     attn_item<0>(p, lds, grp, bh >> 3, bh & 7, qblk, dry);
.LBB0_415:
	s_cmp_gt_i32 s24, 3
	s_cselect_b64 s[0:1], -1, 0
	s_cmp_lt_i32 s25, 4
	s_cselect_b64 s[2:3], -1, 0
	s_or_b64 s[0:1], s[0:1], s[2:3]
	v_bfe_u32 v231, v181, 6, 1
	s_and_b64 vcc, exec, s[0:1]
	v_lshrrev_b32_e32 v232, 2, v181
	v_lshlrev_b32_e32 v188, 6, v231
	v_lshrrev_b32_e32 v233, 3, v181
	v_readlane_b32 s53, v248, 33
	s_cbranch_vccnz .LBB0_524
	s_and_b32 s0, s53, 7
	s_bfe_u32 s30, s26, 0x10003
	s_lshl_b32 s0, s0, 2
	s_add_u32 s0, s96, s0
	s_addc_u32 s1, s97, 0
	s_add_u32 s34, s0, 0x166d800
	s_addc_u32 s35, s1, 0
	s_add_u32 s18, s96, 0x5b7e000
	s_movk_i32 s0, 0xe0
	v_lshlrev_b32_e32 v1, 3, v181
	v_add_u32_e32 v7, 0x100, v181
	v_add_u32_e32 v9, 0x200, v181
	v_add_u32_e32 v11, 0x300, v181
	s_addc_u32 s19, s97, 0
	v_and_or_b32 v147, v232, s0, v189
	v_and_b32_e32 v3, 0x78, v1
	v_lshrrev_b32_e32 v5, 4, v181
	s_movk_i32 s0, 0x440
	v_lshrrev_b32_e32 v8, 4, v7
	v_lshrrev_b32_e32 v10, 4, v9
	v_lshrrev_b32_e32 v12, 4, v11
	s_add_u32 s33, s96, 0xa08e000
	v_mov_b32_e32 v145, 0
	v_mad_u32_u24 v0, v5, s0, v3
	v_mad_u32_u24 v2, v8, s0, v3
	v_mad_u32_u24 v4, v10, s0, v3
	v_mad_u32_u24 v6, v12, s0, v3
	s_movk_i32 s0, 0x210
	s_addc_u32 s28, s97, 0
	v_lshrrev_b32_e32 v171, 3, v9
	v_mul_u32_u24_e32 v176, 0x110, v8
	v_mad_u32_u24 v196, v147, s0, v182
	s_add_u32 s76, s96, 0x1668000
	v_lshl_add_u64 v[8:9], s[96:97], 0, v[144:145]
	s_mov_b64 s[0:1], 0x1668100
	s_addc_u32 s77, s97, 0
	v_lshl_add_u64 v[148:149], v[8:9], 0, s[0:1]
	v_readlane_b32 s0, v248, 0
	v_readlane_b32 s1, v248, 1
	s_add_u32 s16, s0, 0xf0
	s_addc_u32 s17, s1, 0
	s_add_u32 s82, s96, 0x166a400
	s_addc_u32 s83, s97, 0
	v_readlane_b32 s0, v248, 8
	s_cmp_eq_u32 s0, 0
	s_cselect_b64 s[2:3], -1, 0
	s_add_u32 s84, s96, 0x166a500
	s_addc_u32 s85, s97, 0
	v_writelane_b32 v248, s2, 54
	s_cmp_eq_u32 s0, 1
	v_mov_b32_e32 v183, v145
	v_writelane_b32 v248, s3, 55
	s_cselect_b64 s[2:3], -1, 0
	s_add_u32 s86, s96, 0x166a600
	s_addc_u32 s87, s97, 0
	v_writelane_b32 v248, s2, 58
	v_cmp_gt_u32_e32 vcc, 0x80, v181
	s_and_saveexec_b64 s[4:5], vcc
	v_lshlrev_b32_e32 v142, 2, v181
	global_load_dword v143, v142, s[12:13]
	v_add_u32_e32 v142, 0x11800, v142
	s_waitcnt vmcnt(0)
	ds_write_b32 v142, v143
	s_or_b64 exec, exec, s[4:5]
	s_cmp_eq_u32 s0, 2
	v_lshl_add_u64 v[150:151], s[12:13], 0, v[182:183]
	v_writelane_b32 v248, s3, 59
	s_cselect_b64 s[2:3], -1, 0
	s_add_u32 s88, s96, 0x166a700
	s_addc_u32 s89, s97, 0
	v_writelane_b32 v248, s2, 62
	s_cmp_eq_u32 s0, 3
	v_or_b32_e32 v173, 0x12000, v144
	v_writelane_b32 v248, s3, 63
	s_cselect_b64 s[2:3], -1, 0
	s_add_u32 s90, s96, 0x166a800
	s_addc_u32 s91, s97, 0
	v_writelane_b32 v247, s2, 2
	s_cmp_eq_u32 s0, 4
	v_lshlrev_b32_e32 v144, 1, v0
	v_writelane_b32 v247, s3, 3
	s_cselect_b64 s[2:3], -1, 0
	s_add_u32 s92, s96, 0x166a900
	s_addc_u32 s93, s97, 0
	v_writelane_b32 v247, s2, 6
	s_cmp_eq_u32 s0, 5
	v_and_b32_e32 v169, 56, v1
	v_writelane_b32 v247, s3, 7
	s_cselect_b64 s[2:3], -1, 0
	s_add_u32 s94, s96, 0x166aa00
	s_addc_u32 s95, s97, 0
	v_writelane_b32 v247, s2, 10
	s_cmp_eq_u32 s0, 6
	v_lshrrev_b32_e32 v170, 3, v7
	v_writelane_b32 v247, s3, 11
	s_cselect_b64 s[2:3], -1, 0
	s_add_u32 s80, s96, 0x166ab00
	s_addc_u32 s81, s97, 0
	v_writelane_b32 v247, s2, 14
	s_cmp_eq_u32 s0, 7
	v_lshrrev_b32_e32 v172, 3, v11
	v_writelane_b32 v247, s3, 15
	s_cselect_b64 s[2:3], -1, 0
	s_add_u32 s78, s96, 0x166ac00
	s_addc_u32 s79, s97, 0
	v_writelane_b32 v247, s2, 18
	s_cmp_eq_u32 s0, 8
	v_lshlrev_b32_e32 v1, 4, v181
	v_writelane_b32 v247, s3, 19
	s_cselect_b64 s[2:3], -1, 0
	s_add_u32 s4, s96, 0x166ad00
	s_addc_u32 s5, s97, 0
	v_writelane_b32 v247, s2, 22
	s_cmp_eq_u32 s0, 9
	v_mul_u32_u24_e32 v174, 0x110, v5
	v_writelane_b32 v247, s3, 23
	s_cselect_b64 s[2:3], -1, 0
	s_add_u32 s6, s96, 0x166ae00
	s_addc_u32 s7, s97, 0
	v_writelane_b32 v247, s2, 26
	s_cmp_eq_u32 s0, 10
	v_and_b32_e32 v175, 0xf0, v1
	v_writelane_b32 v247, s3, 27
	s_cselect_b64 s[2:3], -1, 0
	s_add_u32 s14, s96, 0x166af00
	s_addc_u32 s15, s97, 0
	v_writelane_b32 v247, s2, 30
	s_cmp_eq_u32 s0, 11
	v_mul_u32_u24_e32 v177, 0x110, v10
	v_writelane_b32 v247, s3, 31
	s_cselect_b64 s[2:3], -1, 0
	s_add_u32 s20, s96, 0x166b000
	s_addc_u32 s21, s97, 0
	v_writelane_b32 v247, s2, 34
	s_cmp_eq_u32 s0, 12
	v_mul_u32_u24_e32 v178, 0x110, v12
	v_writelane_b32 v247, s3, 35
	s_cselect_b64 s[2:3], -1, 0
	s_add_u32 s8, s96, 0x166b100
	s_addc_u32 s9, s97, 0
	v_writelane_b32 v247, s2, 38
	s_cmp_eq_u32 s0, 13
	v_mul_u32_u24_e32 v179, 0x90, v233
	v_writelane_b32 v247, s3, 39
	s_cselect_b64 s[2:3], -1, 0
	s_add_u32 s10, s96, 0x166b200
	s_addc_u32 s11, s97, 0
	v_writelane_b32 v247, s2, 42
	s_cmp_eq_u32 s0, 14
	v_and_b32_e32 v187, 0x70, v1
	v_writelane_b32 v247, s3, 43
	s_cselect_b64 s[2:3], -1, 0
	s_add_u32 s12, s96, 0x166b300
	s_addc_u32 s13, s97, 0
	v_writelane_b32 v247, s2, 46
	s_cmp_eq_u32 s0, 15
	s_cselect_b64 s[36:37], -1, 0
	v_writelane_b32 v247, s3, 47
	s_lshl_b32 s0, s0, 8
	v_readlane_b32 s2, v248, 6
	v_readlane_b32 s3, v248, 7
	s_add_u32 s0, s2, s0
	s_addc_u32 s1, s3, 0
	s_add_u32 s2, s0, 0x1400
	s_addc_u32 s3, s1, 0
	s_add_u32 s22, s0, 0x2400
	s_addc_u32 s23, s1, 0
	s_add_u32 s0, s96, 0x166d400
	s_addc_u32 s1, s97, 0
	v_writelane_b32 v246, s0, 14
	v_mul_u32_u24_e32 v190, 0x90, v170
	v_mul_u32_u24_e32 v191, 0x90, v171
	v_writelane_b32 v246, s1, 15
	s_mov_b64 s[0:1], 0xa0b0000
	v_lshl_add_u64 v[152:153], v[144:145], 0, s[0:1]
	v_lshlrev_b32_e32 v144, 1, v2
	v_lshl_add_u64 v[154:155], v[144:145], 0, s[0:1]
	v_lshlrev_b32_e32 v144, 1, v4
	v_lshl_add_u64 v[156:157], v[144:145], 0, s[0:1]
	v_lshlrev_b32_e32 v144, 1, v6
	v_mul_u32_u24_e32 v192, 0x90, v172
	v_lshl_add_u64 v[158:159], v[144:145], 0, s[0:1]
	s_add_u32 s72, s96, 0x166d500
	s_movk_i32 s0, 0xc0
	v_mul_u32_u24_e32 v193, 0x110, v189
	v_lshlrev_b32_e32 v194, 7, v231
	v_mul_u32_u24_e32 v195, 0x90, v189
	v_writelane_b32 v247, s2, 50
	s_addc_u32 s73, s97, 0
	v_mov_b32_e32 v183, 0x12310
	v_lshlrev_b32_e32 v144, 1, v188
	v_lshlrev_b32_e32 v160, 1, v186
	v_lshlrev_b32_e32 v197, 1, v0
	v_lshlrev_b32_e32 v198, 1, v2
	v_lshlrev_b32_e32 v199, 1, v4
	v_lshlrev_b32_e32 v200, 1, v6
	v_add_u32_e32 v201, v174, v175
	v_add_u32_e32 v202, v176, v175
	v_add_u32_e32 v203, v177, v175
	v_add_u32_e32 v204, v178, v175
	v_add_u32_e32 v205, v179, v187
	v_add_u32_e32 v206, v190, v187
	v_add_u32_e32 v207, v191, v187
	v_add_u32_e32 v208, v192, v187
	v_mov_b32_e32 v209, 0x358637bd
	v_mov_b32_e32 v210, 0x12200
	v_mbcnt_hi_u32_b32 v211, -1, v221
	v_mov_b32_e32 v162, 0x12300
	v_mov_b32_e32 v164, 0x12304
	v_cmp_gt_u32_e64 s[38:39], s0, v181
	s_mov_b32 s29, 0
	s_mov_b32 s25, 0
	v_cmp_ne_u32_e64 s[40:41], 0, v223
	v_writelane_b32 v247, s3, 51
	s_branch .LBB0_420

; __device__ __forceinline__ f32x16 mfma32(bf16x8 a, bf16x8 b, f32x16 c) { return __builtin_amdgcn_mfma_f32_32x32x16_bf16(a, b, c, 0, 0, 0); }
; __device__ __forceinline__ int accrow(int reg, int hh) { return (reg & 3) + 8 * (reg >> 2) + 4 * hh; }
; template <int MODE>
; __device__ void attn_item(const Params& p, char* lds, int grp  , int b, int h, int qblk, int dry) {
;     ...
;       const char* kp0 = base + l31 * KSTR + comp * 128 + hh * 16;
;       {
;         bf16x8 kf0[DQ / 16], kf1[DQ / 16];
; #pragma unroll
;         for (int ks = 0; ks < DQ / 16; ++ks) kf0[ks] = *(const bf16x8*)(kp0 + ks * 32);
;         __builtin_amdgcn_sched_barrier(0);
; #pragma unroll
;         for (int ks = 0; ks < DQ / 16; ++ks) kf1[ks] = *(const bf16x8*)(kp0 + 32 * KSTR + ks * 32);
; #pragma unroll
;         for (int r = 0; r < 16; ++r) { S[0][r] = 0.f; S[1][r] = 0.f; }
; #pragma unroll
;         for (int ks = 0; ks < DQ / 16; ++ks) S[0] = mfma32(kf0[ks], qf[ks], S[0]);
; #pragma unroll
;         for (int ks = 0; ks < DQ / 16; ++ks) S[1] = mfma32(kf1[ks], qf[ks], S[1]);
;       }
;       if (MODE == 0) {
;         const int kpos0 = kt * 64;
;         if (kpos0 + 63 > qpos0 - 91) {
; #pragma unroll
;           for (int sub = 0; sub < 2; ++sub)
; #pragma unroll
;             for (int r = 0; r < 16; ++r) {
;               int rel = kpos0 + sub * 32 + accrow(r, hh) - qpos; rel = rel < -128 ? -128 : rel;
;               S[sub][r] += s_bt[rel + 128];
;             }
;         }
.LBB0_450:
	s_bitcmp1_b32 s27, 0
	s_cselect_b32 s27, 0x8c00, 0
	v_add_u32_e32 v64, s27, v193
	v_add3_u32 v220, v64, v194, v182
	ds_read_b128 v[64:67], v220
	ds_read_b128 v[68:71], v220 offset:32
	ds_read_b128 v[72:75], v220 offset:64
	ds_read_b128 v[76:79], v220 offset:96
	s_waitcnt lgkmcnt(3)
	v_mfma_f32_32x32x16_bf16 v[80:95], v[64:67], v[96:99], 0
	ds_read_b128 v[64:67], v220 offset:8704
	ds_read_b128 v[216:219], v220 offset:8736
	ds_read_b128 v[238:241], v220 offset:8768
	ds_read_b128 v[242:245], v220 offset:8800
	s_add_i32 s44, s24, -1
	s_cmp_le_i32 s44, s2
	s_waitcnt lgkmcnt(6)
	v_mfma_f32_32x32x16_bf16 v[80:95], v[68:71], v[100:103], v[80:95]
	s_waitcnt lgkmcnt(5)
	v_mfma_f32_32x32x16_bf16 v[80:95], v[72:75], v[104:107], v[80:95]
	s_waitcnt lgkmcnt(4)
	v_mfma_f32_32x32x16_bf16 v[80:95], v[76:79], v[108:111], v[80:95]
	s_waitcnt lgkmcnt(3)
	v_mfma_f32_32x32x16_bf16 v[64:79], v[64:67], v[96:99], 0
	s_waitcnt lgkmcnt(2)
	v_mfma_f32_32x32x16_bf16 v[64:79], v[216:219], v[100:103], v[64:79]
	s_waitcnt lgkmcnt(1)
	v_mfma_f32_32x32x16_bf16 v[64:79], v[238:241], v[104:107], v[64:79]
	s_waitcnt lgkmcnt(0)
	v_mfma_f32_32x32x16_bf16 v[64:79], v[242:245], v[108:111], v[64:79]
	s_cbranch_scc1 .LBB0_452
	v_add_u32_e32 v220, s24, v165
	v_subrev_u32_e32 v216, 64, v220
	v_max_i32_e32 v216, 0xffffff80, v216
	v_lshl_add_u32 v238, v216, 2, v210
	v_subrev_u32_e32 v216, 63, v220
	v_max_i32_e32 v216, 0xffffff80, v216
	v_lshl_add_u32 v239, v216, 2, v210
	v_subrev_u32_e32 v216, 62, v220
	v_max_i32_e32 v216, 0xffffff80, v216
	v_lshl_add_u32 v240, v216, 2, v210
	v_subrev_u32_e32 v216, 61, v220
	v_max_i32_e32 v216, 0xffffff80, v216
	v_lshl_add_u32 v241, v216, 2, v210
	v_subrev_u32_e32 v216, 56, v220
	v_max_i32_e32 v216, 0xffffff80, v216
	v_lshl_add_u32 v242, v216, 2, v210
	v_subrev_u32_e32 v216, 55, v220
	v_max_i32_e32 v216, 0xffffff80, v216
	v_lshl_add_u32 v243, v216, 2, v210
	v_subrev_u32_e32 v216, 54, v220
	v_max_i32_e32 v216, 0xffffff80, v216
	v_lshl_add_u32 v244, v216, 2, v210
	v_subrev_u32_e32 v216, 53, v220
	v_max_i32_e32 v216, 0xffffff80, v216
	v_lshl_add_u32 v245, v216, 2, v210
	v_subrev_u32_e32 v216, 48, v220
	v_subrev_u32_e32 v217, 47, v220
	v_subrev_u32_e32 v218, 46, v220
	v_subrev_u32_e32 v219, 45, v220
	v_subrev_u32_e32 v234, 40, v220
	v_subrev_u32_e32 v235, 39, v220
	v_subrev_u32_e32 v236, 38, v220
	v_subrev_u32_e32 v237, 37, v220
	v_max_i32_e32 v216, 0xffffff80, v216
	v_max_i32_e32 v217, 0xffffff80, v217
	v_max_i32_e32 v218, 0xffffff80, v218
	v_max_i32_e32 v219, 0xffffff80, v219
	v_max_i32_e32 v234, 0xffffff80, v234
	v_max_i32_e32 v235, 0xffffff80, v235
	v_max_i32_e32 v236, 0xffffff80, v236
	v_max_i32_e32 v237, 0xffffff80, v237
	v_lshl_add_u32 v216, v216, 2, v210
	v_lshl_add_u32 v217, v217, 2, v210
	v_lshl_add_u32 v218, v218, 2, v210
	v_lshl_add_u32 v219, v219, 2, v210
	v_lshl_add_u32 v234, v234, 2, v210
	v_lshl_add_u32 v235, v235, 2, v210
	v_lshl_add_u32 v236, v236, 2, v210
	v_lshl_add_u32 v237, v237, 2, v210
	ds_read_b32 v216, v216
	ds_read_b32 v217, v217
	ds_read_b32 v218, v218
	ds_read_b32 v219, v219
	ds_read_b32 v234, v234
	ds_read_b32 v235, v235
	ds_read_b32 v236, v236
	ds_read_b32 v237, v237
	ds_read_b32 v238, v238
	ds_read_b32 v239, v239
	ds_read_b32 v240, v240
	ds_read_b32 v241, v241
	ds_read_b32 v242, v242
	ds_read_b32 v243, v243
	ds_read_b32 v244, v244
	ds_read_b32 v245, v245
	s_waitcnt lgkmcnt(14)
	v_pk_add_f32 v[88:89], v[88:89], v[216:217]
	v_subrev_u32_e32 v216, 32, v220
	v_max_i32_e32 v216, 0xffffff80, v216
	s_waitcnt lgkmcnt(6)
	v_pk_add_f32 v[80:81], v[80:81], v[238:239]
	v_lshl_add_u32 v238, v216, 2, v210
	v_subrev_u32_e32 v216, 31, v220
	v_max_i32_e32 v216, 0xffffff80, v216
	v_lshl_add_u32 v239, v216, 2, v210
	v_subrev_u32_e32 v216, 30, v220
	v_max_i32_e32 v216, 0xffffff80, v216
	s_waitcnt lgkmcnt(4)
	v_pk_add_f32 v[82:83], v[82:83], v[240:241]
	v_lshl_add_u32 v240, v216, 2, v210
	v_subrev_u32_e32 v216, 29, v220
	v_max_i32_e32 v216, 0xffffff80, v216
	v_lshl_add_u32 v241, v216, 2, v210
	v_subrev_u32_e32 v216, 24, v220
	v_max_i32_e32 v216, 0xffffff80, v216
	s_waitcnt lgkmcnt(2)
	v_pk_add_f32 v[84:85], v[84:85], v[242:243]
	v_lshl_add_u32 v242, v216, 2, v210
	v_subrev_u32_e32 v216, 23, v220
	v_max_i32_e32 v216, 0xffffff80, v216
	v_lshl_add_u32 v243, v216, 2, v210
	v_subrev_u32_e32 v216, 22, v220
	v_max_i32_e32 v216, 0xffffff80, v216
	s_waitcnt lgkmcnt(0)
	v_pk_add_f32 v[86:87], v[86:87], v[244:245]
	v_lshl_add_u32 v244, v216, 2, v210
	v_subrev_u32_e32 v216, 21, v220
	v_max_i32_e32 v216, 0xffffff80, v216
	v_pk_add_f32 v[94:95], v[94:95], v[236:237]
	v_pk_add_f32 v[92:93], v[92:93], v[234:235]
	v_pk_add_f32 v[90:91], v[90:91], v[218:219]
	v_lshl_add_u32 v245, v216, 2, v210
	v_add_u32_e32 v216, -16, v220
	v_add_u32_e32 v217, -15, v220
	v_add_u32_e32 v218, -14, v220
	v_add_u32_e32 v219, -13, v220
	v_add_u32_e32 v234, -8, v220
	v_add_u32_e32 v235, -7, v220
	v_add_u32_e32 v236, -6, v220
	v_max_i32_e32 v216, 0xffffff80, v216
	v_max_i32_e32 v217, 0xffffff80, v217
	v_max_i32_e32 v218, 0xffffff80, v218
	v_max_i32_e32 v219, 0xffffff80, v219
	v_max_i32_e32 v234, 0xffffff80, v234
	v_max_i32_e32 v235, 0xffffff80, v235
	v_max_i32_e32 v236, 0xffffff80, v236
	v_add_u32_e32 v220, -5, v220
	v_lshl_add_u32 v216, v216, 2, v210
	v_lshl_add_u32 v217, v217, 2, v210
	v_lshl_add_u32 v218, v218, 2, v210
	v_lshl_add_u32 v219, v219, 2, v210
	v_lshl_add_u32 v234, v234, 2, v210
	v_lshl_add_u32 v235, v235, 2, v210
	v_lshl_add_u32 v236, v236, 2, v210
	v_max_i32_e32 v220, 0xffffff80, v220
	v_lshl_add_u32 v220, v220, 2, v210
	ds_read_b32 v216, v216
	ds_read_b32 v217, v217
	ds_read_b32 v218, v218
	ds_read_b32 v219, v219
	ds_read_b32 v234, v234
	ds_read_b32 v235, v235
	ds_read_b32 v236, v236
	ds_read_b32 v237, v220
	ds_read_b32 v238, v238
	ds_read_b32 v239, v239
	ds_read_b32 v240, v240
	ds_read_b32 v241, v241
	ds_read_b32 v242, v242
	ds_read_b32 v243, v243
	ds_read_b32 v244, v244
	ds_read_b32 v245, v245
	s_waitcnt lgkmcnt(8)
	v_pk_add_f32 v[78:79], v[78:79], v[236:237]
	v_pk_add_f32 v[76:77], v[76:77], v[234:235]
	v_pk_add_f32 v[74:75], v[74:75], v[218:219]
	v_pk_add_f32 v[72:73], v[72:73], v[216:217]
	s_waitcnt lgkmcnt(0)
	v_pk_add_f32 v[70:71], v[70:71], v[244:245]
	v_pk_add_f32 v[68:69], v[68:69], v[242:243]
	v_pk_add_f32 v[66:67], v[66:67], v[240:241]
	v_pk_add_f32 v[64:65], v[64:65], v[238:239]

; __device__ __forceinline__ int accrow(int reg, int hh) { return (reg & 3) + 8 * (reg >> 2) + 4 * hh; }
; template <int MODE>
; __device__ void attn_item(const Params& p, char* lds, int grp  , int b, int h, int qblk, int dry) {
;     ...
;     if (comp == 1) {
; #pragma unroll
;       for (int blk = 0; blk < 4; ++blk)
; #pragma unroll
;         for (int r = 0; r < 16; ++r) xch[(qsub * 32 + l31) * 132 + blk * 32 + accrow(r, hh)] = O[blk][r] * inv * lam;
;     }
;     __syncthreads();
;     if (comp == 0 && !dry) {
;       float ss = 0.f;
; #pragma unroll
;       for (int blk = 0; blk < 4; ++blk)
; #pragma unroll
;         for (int r = 0; r < 16; ++r) { const float v = O[blk][r] * inv - xch[(qsub * 32 + l31) * 132 + blk * 32 + accrow(r, hh)]; O[blk][r] = v; ss += v * v; }
;       ss += __shfl_xor(ss, 32);
.LBB0_462:
	s_or_b64 exec, exec, s[0:1]
	s_waitcnt lgkmcnt(0)
	s_barrier
	s_and_saveexec_b64 s[0:1], s[42:43]
	s_cbranch_execz .LBB0_421
	ds_read_b128 v[66:69], v196 offset:480
	ds_read_b128 v[70:73], v196
	ds_read_b128 v[74:77], v196 offset:448
	ds_read_b128 v[82:85], v196 offset:32
	v_add_u32_e32 v142, 0x11800, v182
	s_waitcnt lgkmcnt(3)
	v_pk_fma_f32 v[66:67], v[28:29], v[64:65], v[66:67] op_sel_hi:[1,0,1] neg_lo:[0,0,1] neg_hi:[0,0,1]
	v_pk_fma_f32 v[28:29], v[30:31], v[64:65], v[68:69] op_sel_hi:[1,0,1] neg_lo:[0,0,1] neg_hi:[0,0,1]
	s_waitcnt lgkmcnt(2)
	v_pk_fma_f32 v[72:73], v[34:35], v[64:65], v[72:73] op_sel_hi:[1,0,1] neg_lo:[0,0,1] neg_hi:[0,0,1]
	v_pk_fma_f32 v[70:71], v[32:33], v[64:65], v[70:71] op_sel_hi:[1,0,1] neg_lo:[0,0,1] neg_hi:[0,0,1]
	ds_read_b128 v[30:33], v196 offset:64
	s_waitcnt lgkmcnt(1)
	v_pk_fma_f32 v[82:83], v[36:37], v[64:65], v[82:83] op_sel_hi:[1,0,1] neg_lo:[0,0,1] neg_hi:[0,0,1]
	ds_read_b128 v[34:37], v196 offset:96
	v_pk_mul_f32 v[90:91], v[70:71], v[70:71]
	v_pk_mul_f32 v[88:89], v[72:73], v[72:73]
	s_waitcnt lgkmcnt(1)
	v_pk_fma_f32 v[42:43], v[42:43], v[64:65], v[32:33] op_sel_hi:[1,0,1] neg_lo:[0,0,1] neg_hi:[0,0,1]
	v_pk_fma_f32 v[40:41], v[40:41], v[64:65], v[30:31] op_sel_hi:[1,0,1] neg_lo:[0,0,1] neg_hi:[0,0,1]
	ds_read_b128 v[30:33], v196 offset:128
	s_waitcnt lgkmcnt(1)
	v_pk_fma_f32 v[46:47], v[46:47], v[64:65], v[36:37] op_sel_hi:[1,0,1] neg_lo:[0,0,1] neg_hi:[0,0,1]
	v_pk_fma_f32 v[44:45], v[44:45], v[64:65], v[34:35] op_sel_hi:[1,0,1] neg_lo:[0,0,1] neg_hi:[0,0,1]
	ds_read_b128 v[34:37], v196 offset:160
	v_pk_mul_f32 v[92:93], v[82:83], v[82:83]
	s_waitcnt lgkmcnt(1)
	v_pk_fma_f32 v[50:51], v[50:51], v[64:65], v[32:33] op_sel_hi:[1,0,1] neg_lo:[0,0,1] neg_hi:[0,0,1]
	v_pk_fma_f32 v[48:49], v[48:49], v[64:65], v[30:31] op_sel_hi:[1,0,1] neg_lo:[0,0,1] neg_hi:[0,0,1]
	ds_read_b128 v[30:33], v196 offset:192
	s_waitcnt lgkmcnt(1)
	v_pk_fma_f32 v[54:55], v[54:55], v[64:65], v[36:37] op_sel_hi:[1,0,1] neg_lo:[0,0,1] neg_hi:[0,0,1]
	v_pk_fma_f32 v[52:53], v[52:53], v[64:65], v[34:35] op_sel_hi:[1,0,1] neg_lo:[0,0,1] neg_hi:[0,0,1]
	ds_read_b128 v[34:37], v196 offset:224
	v_pk_fma_f32 v[38:39], v[38:39], v[64:65], v[84:85] op_sel_hi:[1,0,1] neg_lo:[0,0,1] neg_hi:[0,0,1]
	s_waitcnt lgkmcnt(1)
	v_pk_fma_f32 v[58:59], v[58:59], v[64:65], v[32:33] op_sel_hi:[1,0,1] neg_lo:[0,0,1] neg_hi:[0,0,1]
	v_pk_fma_f32 v[56:57], v[56:57], v[64:65], v[30:31] op_sel_hi:[1,0,1] neg_lo:[0,0,1] neg_hi:[0,0,1]
	ds_read_b128 v[30:33], v196 offset:256
	s_waitcnt lgkmcnt(1)
	v_pk_fma_f32 v[62:63], v[62:63], v[64:65], v[36:37] op_sel_hi:[1,0,1] neg_lo:[0,0,1] neg_hi:[0,0,1]
	v_pk_fma_f32 v[60:61], v[60:61], v[64:65], v[34:35] op_sel_hi:[1,0,1] neg_lo:[0,0,1] neg_hi:[0,0,1]
	ds_read_b128 v[34:37], v196 offset:288
	v_pk_mul_f32 v[84:85], v[38:39], v[38:39]
	s_waitcnt vmcnt(3) lgkmcnt(1)
	v_pk_fma_f32 v[118:119], v[2:3], v[64:65], v[32:33] op_sel_hi:[1,0,1] neg_lo:[0,0,1] neg_hi:[0,0,1]
	s_waitcnt vmcnt(2)
	v_pk_fma_f32 v[122:123], v[0:1], v[64:65], v[30:31] op_sel_hi:[1,0,1] neg_lo:[0,0,1] neg_hi:[0,0,1]
	ds_read_b128 v[0:3], v196 offset:320
	s_waitcnt lgkmcnt(1)
	v_pk_fma_f32 v[36:37], v[6:7], v[64:65], v[36:37] op_sel_hi:[1,0,1] neg_lo:[0,0,1] neg_hi:[0,0,1]
	v_pk_fma_f32 v[34:35], v[4:5], v[64:65], v[34:35] op_sel_hi:[1,0,1] neg_lo:[0,0,1] neg_hi:[0,0,1]
	ds_read_b128 v[4:7], v196 offset:352
	ds_read_b128 v[30:33], v196 offset:416
	s_waitcnt lgkmcnt(2)
	v_pk_fma_f32 v[130:131], v[10:11], v[64:65], v[2:3] op_sel_hi:[1,0,1] neg_lo:[0,0,1] neg_hi:[0,0,1]
	v_pk_fma_f32 v[134:135], v[8:9], v[64:65], v[0:1] op_sel_hi:[1,0,1] neg_lo:[0,0,1] neg_hi:[0,0,1]
	ds_read_b128 v[0:3], v196 offset:384
	s_waitcnt lgkmcnt(2)
	v_pk_fma_f32 v[14:15], v[14:15], v[64:65], v[6:7] op_sel_hi:[1,0,1] neg_lo:[0,0,1] neg_hi:[0,0,1]
	s_waitcnt lgkmcnt(1)
	v_pk_fma_f32 v[6:7], v[20:21], v[64:65], v[30:31] op_sel_hi:[1,0,1] neg_lo:[0,0,1] neg_hi:[0,0,1]
	v_add_f32_e32 v30, v90, v91
	v_add_f32_e32 v30, v30, v88
	v_add_f32_e32 v30, v30, v89
	v_add_f32_e32 v30, v30, v92
	v_add_f32_e32 v30, v30, v93
	v_add_f32_e32 v30, v30, v84
	v_pk_mul_f32 v[96:97], v[40:41], v[40:41]
	v_add_f32_e32 v30, v30, v85
	v_add_f32_e32 v30, v30, v96
	v_pk_mul_f32 v[94:95], v[42:43], v[42:43]
	v_add_f32_e32 v30, v30, v97
	v_add_f32_e32 v30, v30, v94
	v_pk_mul_f32 v[100:101], v[44:45], v[44:45]
	v_add_f32_e32 v30, v30, v95
	v_add_f32_e32 v30, v30, v100
	v_pk_mul_f32 v[98:99], v[46:47], v[46:47]
	v_add_f32_e32 v30, v30, v101
	v_add_f32_e32 v30, v30, v98
	v_pk_mul_f32 v[104:105], v[48:49], v[48:49]
	v_add_f32_e32 v30, v30, v99
	v_add_f32_e32 v30, v30, v104
	v_pk_mul_f32 v[102:103], v[50:51], v[50:51]
	v_add_f32_e32 v30, v30, v105
	v_add_f32_e32 v30, v30, v102
	v_pk_mul_f32 v[108:109], v[52:53], v[52:53]
	v_add_f32_e32 v30, v30, v103
	v_add_f32_e32 v30, v30, v108
	v_pk_mul_f32 v[106:107], v[54:55], v[54:55]
	v_add_f32_e32 v30, v30, v109
	v_add_f32_e32 v30, v30, v106
	v_pk_mul_f32 v[112:113], v[56:57], v[56:57]
	v_add_f32_e32 v30, v30, v107
	v_add_f32_e32 v30, v30, v112
	v_pk_mul_f32 v[110:111], v[58:59], v[58:59]
	v_add_f32_e32 v30, v30, v113
	v_add_f32_e32 v30, v30, v110
	v_pk_mul_f32 v[116:117], v[60:61], v[60:61]
	v_add_f32_e32 v30, v30, v111
	v_add_f32_e32 v30, v30, v116
	v_pk_mul_f32 v[114:115], v[62:63], v[62:63]
	v_add_f32_e32 v30, v30, v117
	v_add_f32_e32 v30, v30, v114
	s_waitcnt vmcnt(1)
; __device__ __forceinline__ unsigned pk2(float lo, float hi) { f32v2_t v = {lo, hi}; bf16v2_t r = __builtin_convertvector(v, bf16v2_t); return __builtin_bit_cast(unsigned, r); }
; template <int MODE>
; __device__ void attn_item(const Params& p, char* lds, int grp  , int b, int h, int qblk, int dry) {
;     ...
;       ss += __shfl_xor(ss, 32);
;       const float rs = rsqrtf(ss * (1.f / 128.f) + EPS) * 0.8f;
;       bf16_t* o = (bf16_t*)(ws + W_C) + (size_t)qtok * LDH + h * 128;
;       const float* sg = p.in[10];
; #pragma unroll
;       for (int blk = 0; blk < 4; ++blk)
; #pragma unroll
;         for (int g = 0; g < 4; ++g) {
;           const int dv = blk * 32 + 8 * g + 4 * hh;
;           f32x4 gg = *(const f32x4*)(sg + dv);
;           u32x2 w; w.x = pk2(O[blk][4 * g] * rs * gg[0], O[blk][4 * g + 1] * rs * gg[1]); w.y = pk2(O[blk][4 * g + 2] * rs * gg[2], O[blk][4 * g + 3] * rs * gg[3]);
;           *(u32x2*)(o + dv) = w;
;         }
	v_pk_mul_f32 v[124:125], v[122:123], v[122:123]
	v_add_f32_e32 v30, v30, v115
	v_add_f32_e32 v30, v30, v124
	v_pk_mul_f32 v[120:121], v[118:119], v[118:119]
	v_add_f32_e32 v30, v30, v125
	v_add_f32_e32 v30, v30, v120
	v_pk_mul_f32 v[128:129], v[34:35], v[34:35]
	v_add_f32_e32 v30, v30, v121
	v_add_f32_e32 v30, v30, v128
	v_pk_mul_f32 v[126:127], v[36:37], v[36:37]
	v_add_f32_e32 v30, v30, v129
	v_add_f32_e32 v30, v30, v126
	v_pk_mul_f32 v[136:137], v[134:135], v[134:135]
	v_add_f32_e32 v30, v30, v127
	v_add_f32_e32 v30, v30, v136
	v_pk_mul_f32 v[132:133], v[130:131], v[130:131]
	v_add_f32_e32 v30, v30, v137
	v_pk_fma_f32 v[12:13], v[12:13], v[64:65], v[4:5] op_sel_hi:[1,0,1] neg_lo:[0,0,1] neg_hi:[0,0,1]
	v_add_f32_e32 v30, v30, v132
	v_pk_mul_f32 v[140:141], v[12:13], v[12:13]
	v_add_f32_e32 v30, v30, v133
	v_add_f32_e32 v30, v30, v140
	v_pk_mul_f32 v[138:139], v[14:15], v[14:15]
	v_add_f32_e32 v30, v30, v141
	s_waitcnt lgkmcnt(0)
	v_pk_fma_f32 v[10:11], v[16:17], v[64:65], v[0:1] op_sel_hi:[1,0,1] neg_lo:[0,0,1] neg_hi:[0,0,1]
	v_add_f32_e32 v30, v30, v138
	v_pk_mul_f32 v[16:17], v[10:11], v[10:11]
	v_add_f32_e32 v30, v30, v139
	v_pk_fma_f32 v[8:9], v[18:19], v[64:65], v[2:3] op_sel_hi:[1,0,1] neg_lo:[0,0,1] neg_hi:[0,0,1]
	v_add_f32_e32 v16, v30, v16
	v_pk_mul_f32 v[18:19], v[8:9], v[8:9]
	v_add_f32_e32 v16, v16, v17
	v_add_f32_e32 v16, v16, v18
	v_pk_mul_f32 v[20:21], v[6:7], v[6:7]
	v_add_f32_e32 v16, v16, v19
	v_pk_fma_f32 v[4:5], v[22:23], v[64:65], v[32:33] op_sel_hi:[1,0,1] neg_lo:[0,0,1] neg_hi:[0,0,1]
	v_add_f32_e32 v16, v16, v20
	v_pk_mul_f32 v[22:23], v[4:5], v[4:5]
	v_add_f32_e32 v16, v16, v21
	v_pk_fma_f32 v[2:3], v[24:25], v[64:65], v[74:75] op_sel_hi:[1,0,1] neg_lo:[0,0,1] neg_hi:[0,0,1]
	v_add_f32_e32 v16, v16, v22
	v_pk_mul_f32 v[24:25], v[2:3], v[2:3]
	v_add_f32_e32 v16, v16, v23
	v_pk_fma_f32 v[0:1], v[26:27], v[64:65], v[76:77] op_sel_hi:[1,0,1] neg_lo:[0,0,1] neg_hi:[0,0,1]
	v_add_f32_e32 v16, v16, v24
	v_pk_mul_f32 v[26:27], v[0:1], v[0:1]
	v_add_f32_e32 v16, v16, v25
	v_add_f32_e32 v16, v16, v26
	v_pk_mul_f32 v[68:69], v[66:67], v[66:67]
	v_add_f32_e32 v16, v16, v27
	v_add_f32_e32 v16, v16, v68
	v_pk_mul_f32 v[86:87], v[28:29], v[28:29]
	v_add_f32_e32 v16, v16, v69
	v_add_f32_e32 v16, v16, v86
	v_add_f32_e32 v16, v16, v87
	ds_bpermute_b32 v17, v65, v16
	s_mov_b32 s2, 0x800000
	s_waitcnt lgkmcnt(0)
	ds_read_b128 v[78:81], v142
	v_add_f32_e32 v16, v16, v17
	v_fmamk_f32 v16, v16, 0x3c000000, v209
	v_mul_f32_e32 v17, 0x4b800000, v16
	v_cmp_gt_f32_e32 vcc, s2, v16
	s_nop 1
	v_cndmask_b32_e32 v16, v16, v17, vcc
	v_rsq_f32_e32 v18, v16
	v_lshlrev_b32_e32 v16, 1, v146
	v_mov_b32_e32 v17, v145
	v_lshl_add_u64 v[20:21], v[166:167], 0, v[16:17]
	v_mul_f32_e32 v16, 0x45800000, v18
	v_cndmask_b32_e32 v16, v18, v16, vcc
	v_mul_f32_e32 v22, 0x3f4ccccd, v16
	v_pk_mul_f32 v[16:17], v[70:71], v[22:23] op_sel_hi:[1,0]
	v_pk_mul_f32 v[18:19], v[72:73], v[22:23] op_sel_hi:[1,0]
	s_waitcnt lgkmcnt(0)
	v_pk_mul_f32 v[16:17], v[78:79], v[16:17]
	v_pk_mul_f32 v[18:19], v[80:81], v[18:19]
	v_cvt_pk_bf16_f32 v16, v16, v17
	v_cvt_pk_bf16_f32 v17, v18, v19
	global_store_dwordx2 v[20:21], v[16:17], off
	ds_read_b128 v[16:19], v142 offset:32
	v_pk_mul_f32 v[24:25], v[82:83], v[22:23] op_sel_hi:[1,0]
	v_pk_mul_f32 v[26:27], v[38:39], v[22:23] op_sel_hi:[1,0]
	v_pk_mul_f32 v[12:13], v[12:13], v[22:23] op_sel_hi:[1,0]
	v_pk_mul_f32 v[14:15], v[14:15], v[22:23] op_sel_hi:[1,0]
	v_pk_mul_f32 v[10:11], v[10:11], v[22:23] op_sel_hi:[1,0]
	v_pk_mul_f32 v[8:9], v[8:9], v[22:23] op_sel_hi:[1,0]
	v_pk_mul_f32 v[6:7], v[6:7], v[22:23] op_sel_hi:[1,0]
	v_pk_mul_f32 v[4:5], v[4:5], v[22:23] op_sel_hi:[1,0]
	v_pk_mul_f32 v[2:3], v[2:3], v[22:23] op_sel_hi:[1,0]
	v_pk_mul_f32 v[0:1], v[0:1], v[22:23] op_sel_hi:[1,0]
	s_waitcnt lgkmcnt(0)
	v_pk_mul_f32 v[16:17], v[16:17], v[24:25]
	v_pk_mul_f32 v[18:19], v[18:19], v[26:27]
	v_cvt_pk_bf16_f32 v16, v16, v17
	v_cvt_pk_bf16_f32 v17, v18, v19
	global_store_dwordx2 v[20:21], v[16:17], off offset:16
	ds_read_b128 v[16:19], v142 offset:64
	v_pk_mul_f32 v[24:25], v[40:41], v[22:23] op_sel_hi:[1,0]
	v_pk_mul_f32 v[26:27], v[42:43], v[22:23] op_sel_hi:[1,0]
	s_waitcnt lgkmcnt(0)
	v_pk_mul_f32 v[16:17], v[16:17], v[24:25]
	v_pk_mul_f32 v[18:19], v[18:19], v[26:27]
	v_cvt_pk_bf16_f32 v16, v16, v17
	v_cvt_pk_bf16_f32 v17, v18, v19
	global_store_dwordx2 v[20:21], v[16:17], off offset:32
	ds_read_b128 v[16:19], v142 offset:96
	v_pk_mul_f32 v[24:25], v[44:45], v[22:23] op_sel_hi:[1,0]
	v_pk_mul_f32 v[26:27], v[46:47], v[22:23] op_sel_hi:[1,0]
	s_waitcnt lgkmcnt(0)
; __device__ __forceinline__ unsigned pk2(float lo, float hi) { f32v2_t v = {lo, hi}; bf16v2_t r = __builtin_convertvector(v, bf16v2_t); return __builtin_bit_cast(unsigned, r); }
; template <int MODE>
; __device__ void attn_item(const Params& p, char* lds, int grp  , int b, int h, int qblk, int dry) {
;     ...
; #pragma unroll
;       for (int blk = 0; blk < 4; ++blk)
; #pragma unroll
;         for (int g = 0; g < 4; ++g) {
;           const int dv = blk * 32 + 8 * g + 4 * hh;
;           f32x4 gg = *(const f32x4*)(sg + dv);
;           u32x2 w; w.x = pk2(O[blk][4 * g] * rs * gg[0], O[blk][4 * g + 1] * rs * gg[1]); w.y = pk2(O[blk][4 * g + 2] * rs * gg[2], O[blk][4 * g + 3] * rs * gg[3]);
;           *(u32x2*)(o + dv) = w;
;         }
	v_pk_mul_f32 v[16:17], v[16:17], v[24:25]
	v_pk_mul_f32 v[18:19], v[18:19], v[26:27]
	v_cvt_pk_bf16_f32 v16, v16, v17
	v_cvt_pk_bf16_f32 v17, v18, v19
	global_store_dwordx2 v[20:21], v[16:17], off offset:48
	ds_read_b128 v[16:19], v142 offset:128
	v_pk_mul_f32 v[24:25], v[48:49], v[22:23] op_sel_hi:[1,0]
	v_pk_mul_f32 v[26:27], v[50:51], v[22:23] op_sel_hi:[1,0]
	s_waitcnt lgkmcnt(0)
	v_pk_mul_f32 v[16:17], v[16:17], v[24:25]
	v_pk_mul_f32 v[18:19], v[18:19], v[26:27]
	v_cvt_pk_bf16_f32 v16, v16, v17
	v_cvt_pk_bf16_f32 v17, v18, v19
	global_store_dwordx2 v[20:21], v[16:17], off offset:64
	ds_read_b128 v[16:19], v142 offset:160
	v_pk_mul_f32 v[24:25], v[52:53], v[22:23] op_sel_hi:[1,0]
	v_pk_mul_f32 v[26:27], v[54:55], v[22:23] op_sel_hi:[1,0]
	s_waitcnt lgkmcnt(0)
	v_pk_mul_f32 v[16:17], v[16:17], v[24:25]
	v_pk_mul_f32 v[18:19], v[18:19], v[26:27]
	v_cvt_pk_bf16_f32 v16, v16, v17
	v_cvt_pk_bf16_f32 v17, v18, v19
	global_store_dwordx2 v[20:21], v[16:17], off offset:80
	ds_read_b128 v[16:19], v142 offset:192
	v_pk_mul_f32 v[24:25], v[56:57], v[22:23] op_sel_hi:[1,0]
	v_pk_mul_f32 v[26:27], v[58:59], v[22:23] op_sel_hi:[1,0]
	s_waitcnt lgkmcnt(0)
	v_pk_mul_f32 v[16:17], v[24:25], v[16:17]
	v_pk_mul_f32 v[18:19], v[26:27], v[18:19]
	v_cvt_pk_bf16_f32 v16, v16, v17
	v_cvt_pk_bf16_f32 v17, v18, v19
	global_store_dwordx2 v[20:21], v[16:17], off offset:96
	ds_read_b128 v[16:19], v142 offset:224
	v_pk_mul_f32 v[24:25], v[60:61], v[22:23] op_sel_hi:[1,0]
	v_pk_mul_f32 v[26:27], v[62:63], v[22:23] op_sel_hi:[1,0]
	s_waitcnt lgkmcnt(0)
	v_pk_mul_f32 v[16:17], v[24:25], v[16:17]
	v_pk_mul_f32 v[18:19], v[26:27], v[18:19]
	v_cvt_pk_bf16_f32 v16, v16, v17
	v_cvt_pk_bf16_f32 v17, v18, v19
	global_store_dwordx2 v[20:21], v[16:17], off offset:112
	ds_read_b128 v[16:19], v142 offset:256
	v_pk_mul_f32 v[24:25], v[122:123], v[22:23] op_sel_hi:[1,0]
	v_pk_mul_f32 v[26:27], v[118:119], v[22:23] op_sel_hi:[1,0]
	s_waitcnt lgkmcnt(0)
	v_pk_mul_f32 v[16:17], v[24:25], v[16:17]
	v_pk_mul_f32 v[18:19], v[26:27], v[18:19]
	v_cvt_pk_bf16_f32 v16, v16, v17
	v_cvt_pk_bf16_f32 v17, v18, v19
	global_store_dwordx2 v[20:21], v[16:17], off offset:128
	ds_read_b128 v[16:19], v142 offset:288
	v_pk_mul_f32 v[24:25], v[34:35], v[22:23] op_sel_hi:[1,0]
	v_pk_mul_f32 v[26:27], v[36:37], v[22:23] op_sel_hi:[1,0]
	s_waitcnt lgkmcnt(0)
	v_pk_mul_f32 v[16:17], v[24:25], v[16:17]
	v_pk_mul_f32 v[18:19], v[26:27], v[18:19]
	v_cvt_pk_bf16_f32 v16, v16, v17
	v_cvt_pk_bf16_f32 v17, v18, v19
	global_store_dwordx2 v[20:21], v[16:17], off offset:144
	ds_read_b128 v[16:19], v142 offset:320
	v_pk_mul_f32 v[24:25], v[134:135], v[22:23] op_sel_hi:[1,0]
	v_pk_mul_f32 v[26:27], v[130:131], v[22:23] op_sel_hi:[1,0]
	s_waitcnt lgkmcnt(0)
	v_pk_mul_f32 v[16:17], v[24:25], v[16:17]
	v_pk_mul_f32 v[18:19], v[26:27], v[18:19]
	v_cvt_pk_bf16_f32 v16, v16, v17
	v_cvt_pk_bf16_f32 v17, v18, v19
	global_store_dwordx2 v[20:21], v[16:17], off offset:160
	ds_read_b128 v[16:19], v142 offset:352
	s_waitcnt lgkmcnt(0)
	v_pk_mul_f32 v[12:13], v[12:13], v[16:17]
	v_pk_mul_f32 v[14:15], v[14:15], v[18:19]
	v_cvt_pk_bf16_f32 v12, v12, v13
	v_cvt_pk_bf16_f32 v13, v14, v15
	global_store_dwordx2 v[20:21], v[12:13], off offset:176
	ds_read_b128 v[12:15], v142 offset:384
	s_waitcnt lgkmcnt(0)
	v_pk_mul_f32 v[10:11], v[10:11], v[12:13]
	v_pk_mul_f32 v[8:9], v[8:9], v[14:15]
	v_cvt_pk_bf16_f32 v10, v10, v11
	v_cvt_pk_bf16_f32 v11, v8, v9
	global_store_dwordx2 v[20:21], v[10:11], off offset:192
	ds_read_b128 v[8:11], v142 offset:416
	s_waitcnt lgkmcnt(0)
	v_pk_mul_f32 v[6:7], v[6:7], v[8:9]
	v_pk_mul_f32 v[4:5], v[4:5], v[10:11]
	v_cvt_pk_bf16_f32 v6, v6, v7
	v_cvt_pk_bf16_f32 v7, v4, v5
	global_store_dwordx2 v[20:21], v[6:7], off offset:208
	ds_read_b128 v[4:7], v142 offset:448
	s_waitcnt lgkmcnt(0)
	v_pk_mul_f32 v[2:3], v[2:3], v[4:5]
	v_pk_mul_f32 v[0:1], v[0:1], v[6:7]
	v_cvt_pk_bf16_f32 v2, v2, v3
	v_cvt_pk_bf16_f32 v3, v0, v1
	global_store_dwordx2 v[20:21], v[2:3], off offset:224
	ds_read_b128 v[0:3], v142 offset:480
	v_pk_mul_f32 v[4:5], v[66:67], v[22:23] op_sel_hi:[1,0]
	v_pk_mul_f32 v[6:7], v[28:29], v[22:23] op_sel_hi:[1,0]
	s_waitcnt lgkmcnt(0)
	v_pk_mul_f32 v[0:1], v[4:5], v[0:1]
	v_pk_mul_f32 v[2:3], v[6:7], v[2:3]
	v_cvt_pk_bf16_f32 v0, v0, v1
	v_cvt_pk_bf16_f32 v1, v2, v3
	global_store_dwordx2 v[20:21], v[0:1], off offset:240
	s_branch .LBB0_421

; __device__ void phase_mla_expand(const Params& p, char* lds) {
;     ...
;     } else if (nt < 8) {
;       gemm_mainloop<true>((const bf16_t*)(ws + W_G) + (size_t)m0 * LDK, LDK, (const bf16_t*)(ws + W_WUKV) + (size_t)n0 * LDK, LDK, 128, acc, lds, 2 * ((mt + nt) & 7));
; #pragma unroll
;       for (int i = 0; i < 2; ++i)
; #pragma unroll
;         for (int j = 0; j < 2; ++j) {
;           const int row = m0 + wr * 64 + i * 32 + l31; const int cb = n0 + wc * 64 + j * 32;
;           st_bf16_sw((bf16_t*)(ws + W_D) + (size_t)row * LDH + cb, acc[i][j], hh, 1.f);
;         }
.LBB0_558:
	v_and_b32_e32 v143, 63, v181
	v_lshrrev_b32_e32 v142, 6, v181
	v_and_b32_e32 v108, 31, v143
	v_lshrrev_b32_e32 v109, 5, v143
	v_mul_u32_u24_e32 v108, 0x110, v108
	v_lshlrev_b32_e32 v109, 4, v109
	v_mul_u32_u24_e32 v110, 0x2200, v142
	v_add3_u32 v108, v108, v109, v110
	v_add_u32_e32 v108, 0x8000, v108
	v_add_u32_e32 v109, 0x8000, v110
	v_lshrrev_b32_e32 v110, 3, v143
	v_and_b32_e32 v111, 7, v143
	v_mul_u32_u24_e32 v143, 0x110, v110
	v_add_u32_e32 v109, v109, v143
	v_lshl_add_u32 v109, v111, 5, v109
	s_mul_i32 s0, s38, 0x880
	s_lshl_b32 s1, s39, 1
	s_add_i32 s0, s0, s1
	s_add_i32 s0, s0, 0xa08e000
	v_lshrrev_b32_e32 v144, 1, v142
	v_mul_u32_u24_e32 v144, 0x22000, v144
	v_mul_u32_u24_e32 v145, 0x880, v110
	v_add_u32_e32 v144, v144, v145
	v_and_b32_e32 v145, 1, v142
	v_mul_u32_u24_e32 v145, 0x80, v145
	v_lshl_add_u32 v145, v111, 4, v145
	v_add3_u32 v144, v144, v145, s0
	ds_write_b128 v108, v[48:51] offset:0
	ds_write_b128 v108, v[52:55] offset:32
	ds_write_b128 v108, v[56:59] offset:64
	ds_write_b128 v108, v[60:63] offset:96
	ds_write_b128 v108, v[32:35] offset:128
	ds_write_b128 v108, v[36:39] offset:160
	ds_write_b128 v108, v[40:43] offset:192
	ds_write_b128 v108, v[44:47] offset:224
	s_waitcnt lgkmcnt(0)
	ds_read_b128 v[32:35], v109 offset:0
	ds_read_b128 v[36:39], v109 offset:16
	ds_read_b128 v[40:43], v109 offset:2176
	ds_read_b128 v[44:47], v109 offset:2192
	ds_read_b128 v[48:51], v109 offset:4352
	ds_read_b128 v[52:55], v109 offset:4368
	ds_read_b128 v[56:59], v109 offset:6528
	ds_read_b128 v[60:63], v109 offset:6544
	s_waitcnt lgkmcnt(6)
	v_cvt_pk_bf16_f32 v32, v32, v33
	v_cvt_pk_bf16_f32 v33, v34, v35
	v_cvt_pk_bf16_f32 v34, v36, v37
	v_cvt_pk_bf16_f32 v35, v38, v39
	global_store_dwordx4 v144, v[32:35], s[96:97]
	v_add_u32_e32 v144, 0x4400, v144
	s_waitcnt lgkmcnt(4)
	v_cvt_pk_bf16_f32 v40, v40, v41
	v_cvt_pk_bf16_f32 v41, v42, v43
	v_cvt_pk_bf16_f32 v42, v44, v45
	v_cvt_pk_bf16_f32 v43, v46, v47
	global_store_dwordx4 v144, v[40:43], s[96:97]
	v_add_u32_e32 v144, 0x4400, v144
	s_waitcnt lgkmcnt(2)
	v_cvt_pk_bf16_f32 v48, v48, v49
	v_cvt_pk_bf16_f32 v49, v50, v51
	v_cvt_pk_bf16_f32 v50, v52, v53
	v_cvt_pk_bf16_f32 v51, v54, v55
	global_store_dwordx4 v144, v[48:51], s[96:97]
	v_add_u32_e32 v144, 0x4400, v144
	s_waitcnt lgkmcnt(0)
	v_cvt_pk_bf16_f32 v56, v56, v57
	v_cvt_pk_bf16_f32 v57, v58, v59
	v_cvt_pk_bf16_f32 v58, v60, v61
	v_cvt_pk_bf16_f32 v59, v62, v63
	global_store_dwordx4 v144, v[56:59], s[96:97]
	v_add_u32_e32 v144, 0x4400, v144
	ds_write_b128 v108, v[16:19] offset:0
	ds_write_b128 v108, v[20:23] offset:32
	ds_write_b128 v108, v[24:27] offset:64
	ds_write_b128 v108, v[28:31] offset:96
	ds_write_b128 v108, v[0:3] offset:128
	ds_write_b128 v108, v[4:7] offset:160
	ds_write_b128 v108, v[8:11] offset:192
	ds_write_b128 v108, v[12:15] offset:224
	s_waitcnt lgkmcnt(0)
	ds_read_b128 v[0:3], v109 offset:0
	ds_read_b128 v[4:7], v109 offset:16
	ds_read_b128 v[8:11], v109 offset:2176
	ds_read_b128 v[12:15], v109 offset:2192
	ds_read_b128 v[16:19], v109 offset:4352
	ds_read_b128 v[20:23], v109 offset:4368
	ds_read_b128 v[24:27], v109 offset:6528
	ds_read_b128 v[28:31], v109 offset:6544
	s_waitcnt lgkmcnt(6)
	v_cvt_pk_bf16_f32 v0, v0, v1
	v_cvt_pk_bf16_f32 v1, v2, v3
	v_cvt_pk_bf16_f32 v2, v4, v5
	v_cvt_pk_bf16_f32 v3, v6, v7
	global_store_dwordx4 v144, v[0:3], s[96:97]
	v_add_u32_e32 v144, 0x4400, v144
	s_waitcnt lgkmcnt(4)
	v_cvt_pk_bf16_f32 v8, v8, v9
	v_cvt_pk_bf16_f32 v9, v10, v11
	v_cvt_pk_bf16_f32 v10, v12, v13
	v_cvt_pk_bf16_f32 v11, v14, v15
	global_store_dwordx4 v144, v[8:11], s[96:97]
	v_add_u32_e32 v144, 0x4400, v144
	s_waitcnt lgkmcnt(2)
	v_cvt_pk_bf16_f32 v16, v16, v17
	v_cvt_pk_bf16_f32 v17, v18, v19
	v_cvt_pk_bf16_f32 v18, v20, v21
	v_cvt_pk_bf16_f32 v19, v22, v23
	global_store_dwordx4 v144, v[16:19], s[96:97]
	v_add_u32_e32 v144, 0x4400, v144
	s_waitcnt lgkmcnt(0)
	v_cvt_pk_bf16_f32 v24, v24, v25
	v_cvt_pk_bf16_f32 v25, v26, v27
	v_cvt_pk_bf16_f32 v26, v28, v29
	v_cvt_pk_bf16_f32 v27, v30, v31
	global_store_dwordx4 v144, v[24:27], s[96:97]
	v_add_u32_e32 v144, 0x4400, v144

; __device__ void phase_mla_expand(const Params& p, char* lds) {
;     ...
;     if (!setB) {
;       gemm_mainloop<true>((const bf16_t*)(ws + F_CQ) + (size_t)m0 * LDQ, LDQ, (const bf16_t*)(ws + W_WUQ) + (size_t)n0 * LDQ, LDQ, 256, acc, lds, 2 * ((mt + nt) & 7));
;       const float sc = 0.10206207261596577f * LOG2E;
; #pragma unroll
;       for (int i = 0; i < 2; ++i)
; #pragma unroll
;         for (int j = 0; j < 2; ++j) {
;           const int tok = m0 + wr * 64 + i * 32 + l31; const int cb = n0 + wc * 64 + j * 32;
;           if (nt < 8) st_bf16_sw((bf16_t*)(ws + W_B) + (size_t)tok * LDH + cb, acc[i][j], hh, sc);
;           else st_bf16_sw((bf16_t*)(ws + F_ZCQ) + (size_t)tok * 512 + (cb - 1024), acc[i][j], hh, sc);
;         }
.LBB0_567:
	v_and_b32_e32 v143, 63, v181
	v_lshrrev_b32_e32 v142, 6, v181
	v_and_b32_e32 v108, 31, v143
	v_lshrrev_b32_e32 v109, 5, v143
	v_mul_u32_u24_e32 v108, 0x110, v108
	v_lshlrev_b32_e32 v109, 4, v109
	v_mul_u32_u24_e32 v110, 0x2200, v142
	v_add3_u32 v108, v108, v109, v110
	v_add_u32_e32 v108, 0x8000, v108
	v_add_u32_e32 v109, 0x8000, v110
	v_lshrrev_b32_e32 v110, 3, v143
	v_and_b32_e32 v111, 7, v143
	v_mul_u32_u24_e32 v143, 0x110, v110
	v_add_u32_e32 v109, v109, v143
	v_lshl_add_u32 v109, v111, 5, v109
	s_lshl_b32 s1, s39, 1
	s_cmp_gt_i32 s41, 7
	s_cbranch_scc1 .Lp4a_qpe
	s_mul_i32 s0, s38, 0x880
	s_add_i32 s0, s0, s1
	s_add_i32 s0, s0, 0x166e000
	v_lshrrev_b32_e32 v144, 1, v142
	v_mul_u32_u24_e32 v144, 0x22000, v144
	v_mul_u32_u24_e32 v145, 0x880, v110
	v_add_u32_e32 v144, v144, v145
	v_and_b32_e32 v145, 1, v142
	v_mul_u32_u24_e32 v145, 0x80, v145
	v_lshl_add_u32 v145, v111, 4, v145
	v_add3_u32 v144, v144, v145, s0
	ds_write_b128 v108, v[48:51] offset:0
	ds_write_b128 v108, v[52:55] offset:32
	ds_write_b128 v108, v[56:59] offset:64
	ds_write_b128 v108, v[60:63] offset:96
	ds_write_b128 v108, v[32:35] offset:128
	ds_write_b128 v108, v[36:39] offset:160
	ds_write_b128 v108, v[40:43] offset:192
	ds_write_b128 v108, v[44:47] offset:224
	s_waitcnt lgkmcnt(0)
	ds_read_b128 v[32:35], v109 offset:0
	ds_read_b128 v[36:39], v109 offset:16
	ds_read_b128 v[40:43], v109 offset:2176
	ds_read_b128 v[44:47], v109 offset:2192
	ds_read_b128 v[48:51], v109 offset:4352
	ds_read_b128 v[52:55], v109 offset:4368
	ds_read_b128 v[56:59], v109 offset:6528
	ds_read_b128 v[60:63], v109 offset:6544
	s_waitcnt lgkmcnt(6)
	v_pk_mul_f32 v[32:33], v[32:33], s[18:19] op_sel_hi:[1,0]
	v_pk_mul_f32 v[34:35], v[34:35], s[18:19] op_sel_hi:[1,0]
	v_pk_mul_f32 v[36:37], v[36:37], s[18:19] op_sel_hi:[1,0]
	v_pk_mul_f32 v[38:39], v[38:39], s[18:19] op_sel_hi:[1,0]
	v_cvt_pk_bf16_f32 v32, v32, v33
	v_cvt_pk_bf16_f32 v33, v34, v35
	v_cvt_pk_bf16_f32 v34, v36, v37
	v_cvt_pk_bf16_f32 v35, v38, v39
	global_store_dwordx4 v144, v[32:35], s[96:97]
	v_add_u32_e32 v144, 0x4400, v144
	s_waitcnt lgkmcnt(4)
	v_pk_mul_f32 v[40:41], v[40:41], s[18:19] op_sel_hi:[1,0]
	v_pk_mul_f32 v[42:43], v[42:43], s[18:19] op_sel_hi:[1,0]
	v_pk_mul_f32 v[44:45], v[44:45], s[18:19] op_sel_hi:[1,0]
	v_pk_mul_f32 v[46:47], v[46:47], s[18:19] op_sel_hi:[1,0]
	v_cvt_pk_bf16_f32 v40, v40, v41
	v_cvt_pk_bf16_f32 v41, v42, v43
	v_cvt_pk_bf16_f32 v42, v44, v45
	v_cvt_pk_bf16_f32 v43, v46, v47
	global_store_dwordx4 v144, v[40:43], s[96:97]
	v_add_u32_e32 v144, 0x4400, v144
	s_waitcnt lgkmcnt(2)
	v_pk_mul_f32 v[48:49], v[48:49], s[18:19] op_sel_hi:[1,0]
	v_pk_mul_f32 v[50:51], v[50:51], s[18:19] op_sel_hi:[1,0]
	v_pk_mul_f32 v[52:53], v[52:53], s[18:19] op_sel_hi:[1,0]
	v_pk_mul_f32 v[54:55], v[54:55], s[18:19] op_sel_hi:[1,0]
	v_cvt_pk_bf16_f32 v48, v48, v49
	v_cvt_pk_bf16_f32 v49, v50, v51
	v_cvt_pk_bf16_f32 v50, v52, v53
	v_cvt_pk_bf16_f32 v51, v54, v55
	global_store_dwordx4 v144, v[48:51], s[96:97]
	v_add_u32_e32 v144, 0x4400, v144
	s_waitcnt lgkmcnt(0)
	v_pk_mul_f32 v[56:57], v[56:57], s[18:19] op_sel_hi:[1,0]
	v_pk_mul_f32 v[58:59], v[58:59], s[18:19] op_sel_hi:[1,0]
	v_pk_mul_f32 v[60:61], v[60:61], s[18:19] op_sel_hi:[1,0]
	v_pk_mul_f32 v[62:63], v[62:63], s[18:19] op_sel_hi:[1,0]
	v_cvt_pk_bf16_f32 v56, v56, v57
	v_cvt_pk_bf16_f32 v57, v58, v59
	v_cvt_pk_bf16_f32 v58, v60, v61
	v_cvt_pk_bf16_f32 v59, v62, v63
	global_store_dwordx4 v144, v[56:59], s[96:97]
	v_add_u32_e32 v144, 0x4400, v144
	ds_write_b128 v108, v[16:19] offset:0
	ds_write_b128 v108, v[20:23] offset:32
	ds_write_b128 v108, v[24:27] offset:64
	ds_write_b128 v108, v[28:31] offset:96
	ds_write_b128 v108, v[0:3] offset:128
	ds_write_b128 v108, v[4:7] offset:160
	ds_write_b128 v108, v[8:11] offset:192
	ds_write_b128 v108, v[12:15] offset:224
	s_waitcnt lgkmcnt(0)
	ds_read_b128 v[0:3], v109 offset:0
	ds_read_b128 v[4:7], v109 offset:16
	ds_read_b128 v[8:11], v109 offset:2176
	ds_read_b128 v[12:15], v109 offset:2192
	ds_read_b128 v[16:19], v109 offset:4352
	ds_read_b128 v[20:23], v109 offset:4368
	ds_read_b128 v[24:27], v109 offset:6528
	ds_read_b128 v[28:31], v109 offset:6544
	s_waitcnt lgkmcnt(6)
	v_pk_mul_f32 v[0:1], v[0:1], s[18:19] op_sel_hi:[1,0]
	v_pk_mul_f32 v[2:3], v[2:3], s[18:19] op_sel_hi:[1,0]
	v_pk_mul_f32 v[4:5], v[4:5], s[18:19] op_sel_hi:[1,0]
	v_pk_mul_f32 v[6:7], v[6:7], s[18:19] op_sel_hi:[1,0]
	v_cvt_pk_bf16_f32 v0, v0, v1
	v_cvt_pk_bf16_f32 v1, v2, v3
	v_cvt_pk_bf16_f32 v2, v4, v5
	v_cvt_pk_bf16_f32 v3, v6, v7
	global_store_dwordx4 v144, v[0:3], s[96:97]
	v_add_u32_e32 v144, 0x4400, v144
	s_waitcnt lgkmcnt(4)
	v_pk_mul_f32 v[8:9], v[8:9], s[18:19] op_sel_hi:[1,0]
	v_pk_mul_f32 v[10:11], v[10:11], s[18:19] op_sel_hi:[1,0]
	v_pk_mul_f32 v[12:13], v[12:13], s[18:19] op_sel_hi:[1,0]
	v_pk_mul_f32 v[14:15], v[14:15], s[18:19] op_sel_hi:[1,0]
	v_cvt_pk_bf16_f32 v8, v8, v9
	v_cvt_pk_bf16_f32 v9, v10, v11
	v_cvt_pk_bf16_f32 v10, v12, v13
	v_cvt_pk_bf16_f32 v11, v14, v15
	global_store_dwordx4 v144, v[8:11], s[96:97]
	v_add_u32_e32 v144, 0x4400, v144
	s_waitcnt lgkmcnt(2)
	v_pk_mul_f32 v[16:17], v[16:17], s[18:19] op_sel_hi:[1,0]
	v_pk_mul_f32 v[18:19], v[18:19], s[18:19] op_sel_hi:[1,0]
	v_pk_mul_f32 v[20:21], v[20:21], s[18:19] op_sel_hi:[1,0]
	v_pk_mul_f32 v[22:23], v[22:23], s[18:19] op_sel_hi:[1,0]
	v_cvt_pk_bf16_f32 v16, v16, v17
	v_cvt_pk_bf16_f32 v17, v18, v19
	v_cvt_pk_bf16_f32 v18, v20, v21
	v_cvt_pk_bf16_f32 v19, v22, v23
	global_store_dwordx4 v144, v[16:19], s[96:97]
	v_add_u32_e32 v144, 0x4400, v144
	s_waitcnt lgkmcnt(0)
	v_pk_mul_f32 v[24:25], v[24:25], s[18:19] op_sel_hi:[1,0]
	v_pk_mul_f32 v[26:27], v[26:27], s[18:19] op_sel_hi:[1,0]
	v_pk_mul_f32 v[28:29], v[28:29], s[18:19] op_sel_hi:[1,0]
	v_pk_mul_f32 v[30:31], v[30:31], s[18:19] op_sel_hi:[1,0]
	v_cvt_pk_bf16_f32 v24, v24, v25
	v_cvt_pk_bf16_f32 v25, v26, v27
	v_cvt_pk_bf16_f32 v26, v28, v29
	v_cvt_pk_bf16_f32 v27, v30, v31
	global_store_dwordx4 v144, v[24:27], s[96:97]
	v_add_u32_e32 v144, 0x4400, v144
	s_branch .Lp4a_done
; __device__ void phase_mla_expand(const Params& p, char* lds) {
;     ...
;     if (!setB) {
;       gemm_mainloop<true>((const bf16_t*)(ws + F_CQ) + (size_t)m0 * LDQ, LDQ, (const bf16_t*)(ws + W_WUQ) + (size_t)n0 * LDQ, LDQ, 256, acc, lds, 2 * ((mt + nt) & 7));
;       const float sc = 0.10206207261596577f * LOG2E;
; #pragma unroll
;       for (int i = 0; i < 2; ++i)
; #pragma unroll
;         for (int j = 0; j < 2; ++j) {
;           const int tok = m0 + wr * 64 + i * 32 + l31; const int cb = n0 + wc * 64 + j * 32;
;           if (nt < 8) st_bf16_sw((bf16_t*)(ws + W_B) + (size_t)tok * LDH + cb, acc[i][j], hh, sc);
;           else st_bf16_sw((bf16_t*)(ws + F_ZCQ) + (size_t)tok * 512 + (cb - 1024), acc[i][j], hh, sc);
;         }
.Lp4a_qpe:
	s_lshl_b32 s0, s38, 10
	s_add_i32 s0, s0, s1
	s_add_i32 s0, s0, 0x1699d800
	v_lshrrev_b32_e32 v144, 1, v142
	v_mul_u32_u24_e32 v144, 0x10000, v144
	v_mul_u32_u24_e32 v145, 0x400, v110
	v_add_u32_e32 v144, v144, v145
	v_and_b32_e32 v145, 1, v142
	v_mul_u32_u24_e32 v145, 0x80, v145
	v_lshl_add_u32 v145, v111, 4, v145
	v_add3_u32 v144, v144, v145, s0
	ds_write_b128 v108, v[48:51] offset:0
	ds_write_b128 v108, v[52:55] offset:32
	ds_write_b128 v108, v[56:59] offset:64
	ds_write_b128 v108, v[60:63] offset:96
	ds_write_b128 v108, v[32:35] offset:128
	ds_write_b128 v108, v[36:39] offset:160
	ds_write_b128 v108, v[40:43] offset:192
	ds_write_b128 v108, v[44:47] offset:224
	s_waitcnt lgkmcnt(0)
	ds_read_b128 v[32:35], v109 offset:0
	ds_read_b128 v[36:39], v109 offset:16
	ds_read_b128 v[40:43], v109 offset:2176
	ds_read_b128 v[44:47], v109 offset:2192
	ds_read_b128 v[48:51], v109 offset:4352
	ds_read_b128 v[52:55], v109 offset:4368
	ds_read_b128 v[56:59], v109 offset:6528
	ds_read_b128 v[60:63], v109 offset:6544
	s_waitcnt lgkmcnt(6)
	v_pk_mul_f32 v[32:33], v[32:33], s[18:19] op_sel_hi:[1,0]
	v_pk_mul_f32 v[34:35], v[34:35], s[18:19] op_sel_hi:[1,0]
	v_pk_mul_f32 v[36:37], v[36:37], s[18:19] op_sel_hi:[1,0]
	v_pk_mul_f32 v[38:39], v[38:39], s[18:19] op_sel_hi:[1,0]
	v_cvt_pk_bf16_f32 v32, v32, v33
	v_cvt_pk_bf16_f32 v33, v34, v35
	v_cvt_pk_bf16_f32 v34, v36, v37
	v_cvt_pk_bf16_f32 v35, v38, v39
	global_store_dwordx4 v144, v[32:35], s[96:97]
	v_add_u32_e32 v144, 0x2000, v144
	s_waitcnt lgkmcnt(4)
	v_pk_mul_f32 v[40:41], v[40:41], s[18:19] op_sel_hi:[1,0]
	v_pk_mul_f32 v[42:43], v[42:43], s[18:19] op_sel_hi:[1,0]
	v_pk_mul_f32 v[44:45], v[44:45], s[18:19] op_sel_hi:[1,0]
	v_pk_mul_f32 v[46:47], v[46:47], s[18:19] op_sel_hi:[1,0]
	v_cvt_pk_bf16_f32 v40, v40, v41
	v_cvt_pk_bf16_f32 v41, v42, v43
	v_cvt_pk_bf16_f32 v42, v44, v45
	v_cvt_pk_bf16_f32 v43, v46, v47
	global_store_dwordx4 v144, v[40:43], s[96:97]
	v_add_u32_e32 v144, 0x2000, v144
	s_waitcnt lgkmcnt(2)
	v_pk_mul_f32 v[48:49], v[48:49], s[18:19] op_sel_hi:[1,0]
	v_pk_mul_f32 v[50:51], v[50:51], s[18:19] op_sel_hi:[1,0]
	v_pk_mul_f32 v[52:53], v[52:53], s[18:19] op_sel_hi:[1,0]
	v_pk_mul_f32 v[54:55], v[54:55], s[18:19] op_sel_hi:[1,0]
	v_cvt_pk_bf16_f32 v48, v48, v49
	v_cvt_pk_bf16_f32 v49, v50, v51
	v_cvt_pk_bf16_f32 v50, v52, v53
	v_cvt_pk_bf16_f32 v51, v54, v55
	global_store_dwordx4 v144, v[48:51], s[96:97]
	v_add_u32_e32 v144, 0x2000, v144
	s_waitcnt lgkmcnt(0)
	v_pk_mul_f32 v[56:57], v[56:57], s[18:19] op_sel_hi:[1,0]
	v_pk_mul_f32 v[58:59], v[58:59], s[18:19] op_sel_hi:[1,0]
	v_pk_mul_f32 v[60:61], v[60:61], s[18:19] op_sel_hi:[1,0]
	v_pk_mul_f32 v[62:63], v[62:63], s[18:19] op_sel_hi:[1,0]
	v_cvt_pk_bf16_f32 v56, v56, v57
	v_cvt_pk_bf16_f32 v57, v58, v59
	v_cvt_pk_bf16_f32 v58, v60, v61
	v_cvt_pk_bf16_f32 v59, v62, v63
	global_store_dwordx4 v144, v[56:59], s[96:97]
	v_add_u32_e32 v144, 0x2000, v144
	ds_write_b128 v108, v[16:19] offset:0
	ds_write_b128 v108, v[20:23] offset:32
	ds_write_b128 v108, v[24:27] offset:64
	ds_write_b128 v108, v[28:31] offset:96
	ds_write_b128 v108, v[0:3] offset:128
	ds_write_b128 v108, v[4:7] offset:160
	ds_write_b128 v108, v[8:11] offset:192
	ds_write_b128 v108, v[12:15] offset:224
	s_waitcnt lgkmcnt(0)
	ds_read_b128 v[0:3], v109 offset:0
	ds_read_b128 v[4:7], v109 offset:16
	ds_read_b128 v[8:11], v109 offset:2176
	ds_read_b128 v[12:15], v109 offset:2192
	ds_read_b128 v[16:19], v109 offset:4352
	ds_read_b128 v[20:23], v109 offset:4368
	ds_read_b128 v[24:27], v109 offset:6528
	ds_read_b128 v[28:31], v109 offset:6544
	s_waitcnt lgkmcnt(6)
	v_pk_mul_f32 v[0:1], v[0:1], s[18:19] op_sel_hi:[1,0]
	v_pk_mul_f32 v[2:3], v[2:3], s[18:19] op_sel_hi:[1,0]
	v_pk_mul_f32 v[4:5], v[4:5], s[18:19] op_sel_hi:[1,0]
	v_pk_mul_f32 v[6:7], v[6:7], s[18:19] op_sel_hi:[1,0]
	v_cvt_pk_bf16_f32 v0, v0, v1
	v_cvt_pk_bf16_f32 v1, v2, v3
	v_cvt_pk_bf16_f32 v2, v4, v5
	v_cvt_pk_bf16_f32 v3, v6, v7
	global_store_dwordx4 v144, v[0:3], s[96:97]
	v_add_u32_e32 v144, 0x2000, v144
	s_waitcnt lgkmcnt(4)
	v_pk_mul_f32 v[8:9], v[8:9], s[18:19] op_sel_hi:[1,0]
	v_pk_mul_f32 v[10:11], v[10:11], s[18:19] op_sel_hi:[1,0]
	v_pk_mul_f32 v[12:13], v[12:13], s[18:19] op_sel_hi:[1,0]
	v_pk_mul_f32 v[14:15], v[14:15], s[18:19] op_sel_hi:[1,0]
	v_cvt_pk_bf16_f32 v8, v8, v9
	v_cvt_pk_bf16_f32 v9, v10, v11
	v_cvt_pk_bf16_f32 v10, v12, v13
	v_cvt_pk_bf16_f32 v11, v14, v15
	global_store_dwordx4 v144, v[8:11], s[96:97]
	v_add_u32_e32 v144, 0x2000, v144
	s_waitcnt lgkmcnt(2)
	v_pk_mul_f32 v[16:17], v[16:17], s[18:19] op_sel_hi:[1,0]
	v_pk_mul_f32 v[18:19], v[18:19], s[18:19] op_sel_hi:[1,0]
	v_pk_mul_f32 v[20:21], v[20:21], s[18:19] op_sel_hi:[1,0]
	v_pk_mul_f32 v[22:23], v[22:23], s[18:19] op_sel_hi:[1,0]
	v_cvt_pk_bf16_f32 v16, v16, v17
	v_cvt_pk_bf16_f32 v17, v18, v19
	v_cvt_pk_bf16_f32 v18, v20, v21
	v_cvt_pk_bf16_f32 v19, v22, v23
	global_store_dwordx4 v144, v[16:19], s[96:97]
	v_add_u32_e32 v144, 0x2000, v144
	s_waitcnt lgkmcnt(0)
	v_pk_mul_f32 v[24:25], v[24:25], s[18:19] op_sel_hi:[1,0]
	v_pk_mul_f32 v[26:27], v[26:27], s[18:19] op_sel_hi:[1,0]
	v_pk_mul_f32 v[28:29], v[28:29], s[18:19] op_sel_hi:[1,0]
	v_pk_mul_f32 v[30:31], v[30:31], s[18:19] op_sel_hi:[1,0]
	v_cvt_pk_bf16_f32 v24, v24, v25
	v_cvt_pk_bf16_f32 v25, v26, v27
	v_cvt_pk_bf16_f32 v26, v28, v29
	v_cvt_pk_bf16_f32 v27, v30, v31
	global_store_dwordx4 v144, v[24:27], s[96:97]
	v_add_u32_e32 v144, 0x2000, v144
.Lp4a_done:
	s_mov_b32 s44, 0

; __device__ __forceinline__ unsigned pk2(float lo, float hi) { f32v2_t v = {lo, hi}; bf16v2_t r = __builtin_convertvector(v, bf16v2_t); return __builtin_bit_cast(unsigned, r); }
; __device__ void phase_ffn_norm(const Params& p) {
;   char* ws = p.ws;
;   const int gtid = blockIdx.x * 256 + threadIdx.x, gthreads = gridDim.x * 256;
;   const int gw = gtid >> 6, nw = gthreads >> 6, lane = threadIdx.x & 63;
;   const float* x1 = (const float*)(ws + D_X1); bf16_t* hf = (bf16_t*)(ws + W_C); const float* g = p.in[19];
;   for (int t = gw; t < T; t += nw) {
;     const float* x = x1 + (size_t)t * DM;
;     f32x4 v[4]; float ss = 0.f;
; #pragma unroll
;     for (int i = 0; i < 4; ++i) { v[i] = *(const f32x4*)(x + i * 256 + lane * 4); ss += v[i][0] * v[i][0] + v[i][1] * v[i][1] + v[i][2] * v[i][2] + v[i][3] * v[i][3]; }
;     ss = wave_sum(ss);
;     const float rs = rsqrtf(ss * (1.f / DM) + EPS);
; #pragma unroll
;     for (int i = 0; i < 4; ++i) {
;       f32x4 gg = *(const f32x4*)(g + i * 256 + lane * 4);
;       u32x2 w; w.x = pk2(v[i][0] * rs * gg[0], v[i][1] * rs * gg[1]); w.y = pk2(v[i][2] * rs * gg[2], v[i][3] * rs * gg[3]);
;       *(u32x2*)(hf + (size_t)t * LDH + i * 256 + lane * 4) = w;
;     }
.LBB0_943:
	s_mov_b64 s[0:1], exec
	v_readlane_b32 s2, v247, 38
	v_readlane_b32 s3, v247, 39
	s_and_b64 s[2:3], s[0:1], s[2:3]
	s_mov_b64 exec, s[2:3]
	s_cbranch_execz .LBB0_946
	v_cmp_lt_i32_e32 vcc, v41, v40
	s_mov_b64 s[2:3], 0
	v_mov_b64_e32 v[34:35], v[24:25]
	v_cndmask_b32_e32 v0, v39, v41, vcc
	v_cmp_lt_i32_e32 vcc, v42, v40
	v_lshlrev_b32_e32 v29, 2, v0
	v_mov_b64_e32 v[36:37], v[20:21]
	v_cndmask_b32_e32 v0, v39, v42, vcc
	v_cmp_lt_i32_e32 vcc, v43, v40
	v_lshlrev_b32_e32 v31, 2, v0
	v_mov_b32_e32 v50, v12
	v_cndmask_b32_e32 v0, v39, v43, vcc
	v_cmp_lt_i32_e32 vcc, v44, v40
	v_lshlrev_b32_e32 v33, 2, v0
	s_nop 0
	v_cndmask_b32_e32 v0, v39, v44, vcc
	v_cmp_lt_i32_e32 vcc, v45, v40
	v_lshlrev_b32_e32 v47, 2, v0
	s_nop 0
	v_cndmask_b32_e32 v0, v39, v45, vcc
	v_cmp_lt_i32_e32 vcc, v46, v40
	v_lshlrev_b32_e32 v48, 2, v0
	s_nop 0
	v_cndmask_b32_e32 v0, v39, v46, vcc
	v_lshlrev_b32_e32 v49, 2, v0
	global_load_dwordx4 v[100:103], v[22:23], off
	global_load_dwordx4 v[104:107], v[22:23], off offset:1024
	global_load_dwordx4 v[108:111], v[22:23], off offset:2048
	global_load_dwordx4 v[112:115], v[22:23], off offset:3072
.LBB0_945:
	v_lshl_add_u64 v[0:1], s[96:97], 0, v[34:35]
	v_add_co_u32_e32 v4, vcc, 0xa08e000, v0
	s_mov_b32 s44, 0x800000
	s_nop 0
	v_addc_co_u32_e32 v5, vcc, 0, v1, vcc
	global_load_dwordx4 v[52:55], v[4:5], off
	global_load_dwordx4 v[0:3], v[4:5], off offset:1024
	global_load_dwordx4 v[8:11], v[4:5], off offset:2048
	global_load_dwordx4 v[4:7], v[4:5], off offset:3072
	v_add_u32_e32 v50, s27, v50
	v_lshl_add_u64 v[34:35], v[34:35], 0, s[18:19]
	s_waitcnt vmcnt(2)
	v_mov_b32_e32 v74, v53
	v_mov_b32_e32 v75, v1
	v_mov_b32_e32 v76, v52
	v_mov_b32_e32 v77, v0
	v_pk_mul_f32 v[74:75], v[74:75], v[74:75]
	s_nop 0
	v_pk_fma_f32 v[76:77], v[76:77], v[76:77], v[74:75]
	v_mov_b32_e32 v74, v54
	v_mov_b32_e32 v75, v2
	v_pk_fma_f32 v[76:77], v[74:75], v[74:75], v[76:77]
	v_mov_b32_e32 v74, v55
	v_mov_b32_e32 v75, v3
	v_pk_fma_f32 v[56:57], v[74:75], v[74:75], v[76:77]
	s_nop 0
	v_add_f32_e32 v14, v56, v57
	s_waitcnt vmcnt(1)
	v_mov_b32_e32 v60, v9
	s_waitcnt vmcnt(0)
	v_mov_b32_e32 v61, v5
	v_mov_b32_e32 v58, v8
	v_mov_b32_e32 v59, v4
	v_pk_mul_f32 v[60:61], v[60:61], v[60:61]
	s_nop 0
	v_pk_fma_f32 v[58:59], v[58:59], v[58:59], v[60:61]
	v_mov_b32_e32 v60, v10
	v_mov_b32_e32 v61, v6
	v_pk_fma_f32 v[58:59], v[60:61], v[60:61], v[58:59]
	v_mov_b32_e32 v60, v11
	v_mov_b32_e32 v61, v7
	v_pk_fma_f32 v[58:59], v[60:61], v[60:61], v[58:59]
	v_lshl_add_u64 v[60:61], s[96:97], 0, v[36:37]
	v_add_f32_e32 v14, v14, v58
	v_add_f32_e32 v14, v14, v59
	ds_bpermute_b32 v51, v29, v14
	v_lshl_add_u64 v[36:37], v[36:37], 0, s[40:41]
	s_waitcnt lgkmcnt(0)
	v_add_f32_e32 v14, v14, v51
	ds_bpermute_b32 v51, v31, v14
	s_waitcnt lgkmcnt(0)
	v_add_f32_e32 v14, v14, v51
	ds_bpermute_b32 v51, v33, v14
	s_waitcnt lgkmcnt(0)
	v_add_f32_e32 v14, v14, v51
	ds_bpermute_b32 v51, v47, v14
	s_waitcnt lgkmcnt(0)
	v_add_f32_e32 v14, v14, v51
	ds_bpermute_b32 v51, v48, v14
	s_waitcnt lgkmcnt(0)
	v_add_f32_e32 v14, v14, v51
	ds_bpermute_b32 v51, v49, v14
	s_waitcnt lgkmcnt(0)
	v_add_f32_e32 v14, v14, v51
	v_fmamk_f32 v14, v14, 0x3a800000, v38
	v_cmp_gt_f32_e32 vcc, s44, v14
	v_mul_f32_e32 v51, 0x4b800000, v14
	s_mov_b32 s44, 0x5b7e000
	v_cndmask_b32_e32 v14, v14, v51, vcc
	v_rsq_f32_e32 v14, v14
	s_nop 0
	v_mul_f32_e32 v51, 0x45800000, v14
	v_cndmask_b32_e32 v14, v14, v51, vcc
	v_pk_mul_f32 v[52:53], v[52:53], v[14:15] op_sel_hi:[1,0]
	v_pk_mul_f32 v[54:55], v[54:55], v[14:15] op_sel_hi:[1,0]
	v_pk_mul_f32 v[0:1], v[0:1], v[14:15] op_sel_hi:[1,0]
	v_pk_mul_f32 v[2:3], v[2:3], v[14:15] op_sel_hi:[1,0]
	v_pk_mul_f32 v[8:9], v[8:9], v[14:15] op_sel_hi:[1,0]
	v_pk_mul_f32 v[4:5], v[4:5], v[14:15] op_sel_hi:[1,0]
	v_pk_mul_f32 v[10:11], v[10:11], v[14:15] op_sel_hi:[1,0]
	v_pk_mul_f32 v[6:7], v[6:7], v[14:15] op_sel_hi:[1,0]
	v_pk_mul_f32 v[52:53], v[100:101], v[52:53]
	v_pk_mul_f32 v[54:55], v[102:103], v[54:55]
	v_add_co_u32_e32 v56, vcc, s44, v60
	v_cvt_pk_bf16_f32 v52, v52, v53
	v_cvt_pk_bf16_f32 v53, v54, v55
	v_addc_co_u32_e32 v57, vcc, 0, v61, vcc
	global_store_dwordx2 v[56:57], v[52:53], off
	s_mov_b32 s44, 0x81ff
	v_cmp_lt_i32_e32 vcc, s44, v50
	s_or_b64 s[2:3], vcc, s[2:3]
	v_pk_mul_f32 v[0:1], v[104:105], v[0:1]
	v_pk_mul_f32 v[2:3], v[106:107], v[2:3]
	v_pk_mul_f32 v[8:9], v[108:109], v[8:9]
	v_pk_mul_f32 v[10:11], v[110:111], v[10:11]
	v_cvt_pk_bf16_f32 v0, v0, v1
	v_cvt_pk_bf16_f32 v1, v2, v3
	global_store_dwordx2 v[56:57], v[0:1], off offset:512
	v_pk_mul_f32 v[4:5], v[112:113], v[4:5]
	v_pk_mul_f32 v[6:7], v[114:115], v[6:7]
	v_cvt_pk_bf16_f32 v8, v8, v9
	v_cvt_pk_bf16_f32 v9, v10, v11
	global_store_dwordx2 v[56:57], v[8:9], off offset:1024
	v_cvt_pk_bf16_f32 v4, v4, v5
	v_cvt_pk_bf16_f32 v5, v6, v7
	global_store_dwordx2 v[56:57], v[4:5], off offset:1536
	s_andn2_b64 exec, exec, s[2:3]
	s_cbranch_execnz .LBB0_945
